# memory-attention units: query and gate fragment loads issued right after the K/V loads (before the staging waits) instead of after the staging barrier
# baseline (speedup 1.0000x reference)
.LBB0_547:
	s_ashr_i32 s38, s40, 7
	s_lshl_b32 s24, s38, 8
	s_add_i32 s42, s24, s30
	s_ashr_i32 s43, s42, 31
	s_lshl_b64 s[42:43], s[42:43], 10
	s_add_u32 s39, s22, s42
	s_addc_u32 s41, s23, s43
	s_and_b32 s24, s14, 0x180
	s_lshl_b32 s24, s24, 1
	s_add_u32 s44, s39, s24
	s_addc_u32 s45, s41, 0
	v_mov_b32_e32 v211, v208
	s_add_u32 s39, s31, s42
	s_addc_u32 s41, s21, s43
	s_waitcnt vmcnt(0)
	v_ashrrev_i32_e32 v62, 5, v211
	v_and_b32_e32 v69, -8, v62
	s_add_u32 s42, s39, s24
	v_and_b32_e32 v68, 0xff, v211
	v_lshlrev_b32_e32 v4, 3, v69
	s_addc_u32 s43, s41, 0
	v_lshlrev_b32_e32 v2, 10, v68
	v_ashrrev_i32_e32 v5, 31, v4
	v_or_b32_e32 v70, 1, v69
	v_lshl_add_u64 v[60:61], s[44:45], 0, v[2:3]
	v_lshl_add_u64 v[64:65], s[42:43], 0, v[2:3]
	v_lshlrev_b64 v[8:9], 1, v[4:5]
	v_lshlrev_b32_e32 v16, 3, v70
	v_or_b32_e32 v71, 2, v69
	v_or_b32_e32 v73, 4, v69
	v_lshl_add_u64 v[28:29], v[60:61], 0, v[8:9]
	v_lshl_add_u64 v[8:9], v[64:65], 0, v[8:9]
	v_ashrrev_i32_e32 v17, 31, v16
	v_lshlrev_b32_e32 v24, 3, v71
	v_or_b32_e32 v72, 3, v69
	v_lshlrev_b32_e32 v36, 3, v73
	global_load_dwordx4 v[4:7], v[28:29], off
	s_nop 0
	global_load_dwordx4 v[8:11], v[8:9], off
	s_nop 0
	global_load_dwordx4 v[12:15], v[28:29], off offset:16
	v_lshl_add_u64 v[16:17], v[16:17], 1, v[64:65]
	v_ashrrev_i32_e32 v25, 31, v24
	v_lshlrev_b32_e32 v32, 3, v72
	v_ashrrev_i32_e32 v37, 31, v36
	global_load_dwordx4 v[16:19], v[16:17], off
	s_nop 0
	global_load_dwordx4 v[20:23], v[28:29], off offset:32
	v_lshl_add_u64 v[24:25], v[24:25], 1, v[64:65]
	v_ashrrev_i32_e32 v33, 31, v32
	v_lshlrev_b64 v[40:41], 1, v[36:37]
	v_or_b32_e32 v74, 5, v69
	v_or_b32_e32 v75, 6, v69
	v_or_b32_e32 v76, 7, v62
	global_load_dwordx4 v[24:27], v[24:25], off
	s_nop 0
	global_load_dwordx4 v[28:31], v[28:29], off offset:48
	v_lshl_add_u64 v[32:33], v[32:33], 1, v[64:65]
	v_lshl_add_u64 v[52:53], v[60:61], 0, v[40:41]
	v_lshlrev_b32_e32 v48, 3, v74
	v_lshlrev_b32_e32 v56, 3, v75
	v_lshlrev_b32_e32 v62, 3, v76
	global_load_dwordx4 v[32:35], v[32:33], off
	v_lshl_add_u64 v[40:41], v[64:65], 0, v[40:41]
	global_load_dwordx4 v[36:39], v[52:53], off
	v_ashrrev_i32_e32 v49, 31, v48
	v_ashrrev_i32_e32 v57, 31, v56
	v_ashrrev_i32_e32 v63, 31, v62
	global_load_dwordx4 v[40:43], v[40:41], off
	v_lshl_add_u64 v[48:49], v[48:49], 1, v[64:65]
	global_load_dwordx4 v[44:47], v[52:53], off offset:16
	v_lshl_add_u64 v[56:57], v[56:57], 1, v[64:65]
	v_lshlrev_b64 v[66:67], 1, v[62:63]
	global_load_dwordx4 v[48:51], v[48:49], off
	v_lshl_add_u64 v[60:61], v[60:61], 0, v[66:67]
	global_load_dwordx4 v[56:59], v[56:57], off
	v_lshl_add_u64 v[64:65], v[64:65], 0, v[66:67]
	global_load_dwordx4 v[52:55], v[52:53], off offset:32
	v_mad_u32_u24 v77, v68, s53, 0
	global_load_dwordx4 v[60:63], v[60:61], off
	v_lshl_add_u32 v2, v68, 1, s11
	global_load_dwordx4 v[64:67], v[64:65], off
	v_lshl_add_u32 v78, v69, 4, v77
	v_mad_u64_u32 v[68:69], s[42:43], v69, s77, v[2:3]
	v_lshl_add_u32 v69, v70, 4, v77
	s_ashr_i32 s39, s38, 31
	s_lshl_b64 s[38:39], s[38:39], 13
	s_and_b32 s41, s1, 0x1f00
	s_add_u32 s41, s41, s3
	v_and_b32_e32 v213, 31, v211
	v_bfe_u32 v201, v211, 4, 2
	v_mov_b32_e32 v81, 0
	s_addc_u32 s42, 0, s20
	s_add_u32 s38, s41, s38
	s_addc_u32 s39, s42, s39
	v_or_b32_e32 v80, s38, v213
	v_mov_b64_e32 v[82:83], s[72:73]
	v_mad_u64_u32 v[82:83], s[42:43], v80, s16, v[82:83]
	v_lshrrev_b32_e32 v80, 2, v211
	v_mad_i32_i24 v83, s39, v238, v83
	v_and_b32_e32 v215, 8, v80
	v_lshl_add_u64 v[82:83], v[82:83], 0, s[24:25]
	v_lshlrev_b32_e32 v84, 1, v215
	v_mov_b32_e32 v85, v3
	v_lshl_add_u64 v[82:83], v[82:83], 0, v[84:85]
	v_add_co_u32_e32 v84, vcc, s17, v82
	s_nop 0
	v_addc_co_u32_e32 v85, vcc, 0, v83, vcc
	global_load_dwordx4 v[116:119], v[84:85], off
	v_lshl_add_u64 v[86:87], v[82:83], 0, s[64:65]
	global_load_dwordx4 v[188:191], v[86:87], off offset:32
	global_load_dwordx4 v[184:187], v[86:87], off offset:64
	global_load_dwordx4 v[180:183], v[86:87], off offset:96
	global_load_dwordx4 v[176:179], v[86:87], off offset:128
	global_load_dwordx4 v[168:171], v[86:87], off offset:160
	global_load_dwordx4 v[164:167], v[86:87], off offset:192
	s_mul_i32 s41, s39, 0x1800
	s_mul_hi_u32 s42, s38, 0x1800
	s_add_i32 s42, s42, s41
	s_mul_i32 s41, s38, 0x1800
	v_lshrrev_b32_e32 v80, 1, v211
	s_add_u32 s41, s72, s41
	v_and_b32_e32 v80, 16, v80
	v_mul_u32_u24_e32 v82, 0x110, v213
	s_addc_u32 s43, s73, s42
	v_add3_u32 v202, 0, v80, v82
	s_add_u32 s42, s41, s24
	v_mul_u32_u24_e32 v80, 0xc00, v201
	s_addc_u32 s43, s43, 0
	v_lshlrev_b32_e32 v80, 1, v80
	global_load_dwordx4 v[172:175], v[86:87], off offset:224
	v_lshl_add_u64 v[86:87], s[42:43], 0, v[80:81]
	v_lshlrev_b32_e32 v80, 4, v211
	v_and_b32_e32 v80, 0xf0, v80
	v_lshl_add_u64 v[86:87], v[86:87], 0, v[80:81]
	v_add_co_u32_e32 v88, vcc, s17, v86
	s_nop 0
	v_addc_co_u32_e32 v89, vcc, 0, v87, vcc
	v_add_co_u32_e32 v90, vcc, s51, v86
	s_nop 1
	v_addc_co_u32_e32 v91, vcc, 0, v87, vcc
	global_load_dwordx4 v[160:163], v[88:89], off offset:1024
	global_load_dwordx4 v[156:159], v[90:91], off offset:1024
	v_add_co_u32_e32 v88, vcc, s58, v86
	s_nop 1
	v_addc_co_u32_e32 v89, vcc, 0, v87, vcc
	v_add_co_u32_e32 v90, vcc, s59, v86
	s_nop 1
	v_addc_co_u32_e32 v91, vcc, 0, v87, vcc
	global_load_dwordx4 v[152:155], v[88:89], off offset:1024
	global_load_dwordx4 v[148:151], v[90:91], off offset:1024
	v_add_co_u32_e32 v88, vcc, s60, v86
	s_nop 1
	v_addc_co_u32_e32 v89, vcc, 0, v87, vcc
	v_add_co_u32_e32 v90, vcc, s61, v86
	s_nop 1
	v_addc_co_u32_e32 v91, vcc, 0, v87, vcc
	global_load_dwordx4 v[144:147], v[88:89], off offset:1024
	global_load_dwordx4 v[140:143], v[90:91], off offset:1024
	v_add_co_u32_e32 v88, vcc, s63, v86
	s_nop 1
	v_addc_co_u32_e32 v89, vcc, 0, v87, vcc
	v_add_co_u32_e32 v86, vcc, s46, v86
	s_nop 1
	v_addc_co_u32_e32 v87, vcc, 0, v87, vcc
	global_load_dwordx4 v[136:139], v[88:89], off offset:1024
	global_load_dwordx4 v[132:135], v[86:87], off offset:1024
	s_waitcnt vmcnt(31)
	ds_write_b128 v78, v[4:7]
	s_waitcnt vmcnt(30)
	ds_write_b16 v68, v8
	ds_write_b16_d16_hi v68, v8 offset:520
	ds_write_b16 v68, v9 offset:1040
	ds_write_b16_d16_hi v68, v9 offset:1560
	ds_write_b16 v68, v10 offset:2080
	ds_write_b16_d16_hi v68, v10 offset:2600
	ds_write_b16 v68, v11 offset:3120
	ds_write_b16_d16_hi v68, v11 offset:3640
	s_waitcnt vmcnt(29)
	ds_write_b128 v69, v[12:15]
	s_waitcnt vmcnt(28)
	ds_write_b16 v68, v16 offset:4160
	ds_write_b16_d16_hi v68, v16 offset:4680
	ds_write_b16 v68, v17 offset:5200
	ds_write_b16_d16_hi v68, v17 offset:5720
	ds_write_b16 v68, v18 offset:6240
	ds_write_b16_d16_hi v68, v18 offset:6760
	ds_write_b16 v68, v19 offset:7280
	ds_write_b16_d16_hi v68, v19 offset:7800
	v_lshl_add_u32 v4, v71, 4, v77
	s_waitcnt vmcnt(27)
	ds_write_b128 v4, v[20:23]
	s_waitcnt vmcnt(26)
	ds_write_b16 v68, v24 offset:8320
	ds_write_b16_d16_hi v68, v24 offset:8840
	ds_write_b16 v68, v25 offset:9360
	ds_write_b16_d16_hi v68, v25 offset:9880
	ds_write_b16 v68, v26 offset:10400
	ds_write_b16_d16_hi v68, v26 offset:10920
	ds_write_b16 v68, v27 offset:11440
	ds_write_b16_d16_hi v68, v27 offset:11960
	v_lshl_add_u32 v4, v72, 4, v77
	s_waitcnt vmcnt(25)
	ds_write_b128 v4, v[28:31]
	s_waitcnt vmcnt(24)
	ds_write_b16 v68, v32 offset:12480
	ds_write_b16_d16_hi v68, v32 offset:13000
	ds_write_b16 v68, v33 offset:13520
	ds_write_b16_d16_hi v68, v33 offset:14040
	ds_write_b16 v68, v34 offset:14560
	ds_write_b16_d16_hi v68, v34 offset:15080
	ds_write_b16 v68, v35 offset:15600
	ds_write_b16_d16_hi v68, v35 offset:16120
	v_lshl_add_u32 v4, v73, 4, v77
	s_waitcnt vmcnt(23)
	ds_write_b128 v4, v[36:39]
	s_waitcnt vmcnt(22)
	ds_write_b16 v68, v40 offset:16640
	ds_write_b16_d16_hi v68, v40 offset:17160
	ds_write_b16 v68, v41 offset:17680
	ds_write_b16_d16_hi v68, v41 offset:18200
	ds_write_b16 v68, v42 offset:18720
	ds_write_b16_d16_hi v68, v42 offset:19240
	ds_write_b16 v68, v43 offset:19760
	ds_write_b16_d16_hi v68, v43 offset:20280
	v_lshl_add_u32 v4, v74, 4, v77
	s_waitcnt vmcnt(21)
	ds_write_b128 v4, v[44:47]
	s_waitcnt vmcnt(20)
	ds_write_b16 v68, v48 offset:20800
	ds_write_b16_d16_hi v68, v48 offset:21320
	ds_write_b16 v68, v49 offset:21840
	ds_write_b16_d16_hi v68, v49 offset:22360
	ds_write_b16 v68, v50 offset:22880
	ds_write_b16_d16_hi v68, v50 offset:23400
	ds_write_b16 v68, v51 offset:23920
	ds_write_b16_d16_hi v68, v51 offset:24440
	v_lshl_add_u32 v4, v75, 4, v77
	s_waitcnt vmcnt(18)
	ds_write_b128 v4, v[52:55]
	ds_write_b16 v68, v56 offset:24960
	ds_write_b16_d16_hi v68, v56 offset:25480
	ds_write_b16 v68, v57 offset:26000
	ds_write_b16_d16_hi v68, v57 offset:26520
	ds_write_b16 v68, v58 offset:27040
	ds_write_b16_d16_hi v68, v58 offset:27560
	ds_write_b16 v68, v59 offset:28080
	ds_write_b16_d16_hi v68, v59 offset:28600
	v_lshl_add_u32 v4, v76, 4, v77
	s_waitcnt vmcnt(17)
	ds_write_b128 v4, v[60:63]
	v_mad_u64_u32 v[4:5], s[42:43], v76, s77, v[2:3]
	s_waitcnt vmcnt(16)
	ds_write_b16 v4, v64
	ds_write_b16_d16_hi v4, v64 offset:520
	ds_write_b16 v4, v65 offset:1040
	ds_write_b16_d16_hi v4, v65 offset:1560
	ds_write_b16 v4, v66 offset:2080
	ds_write_b16_d16_hi v4, v66 offset:2600
	ds_write_b16 v4, v67 offset:3120
	ds_write_b16_d16_hi v4, v67 offset:3640
	s_waitcnt lgkmcnt(0)
	s_barrier
	v_lshlrev_b32_e32 v2, 4, v211
	v_and_b32_e32 v2, 0xf0, v2
	ds_read_b128 v[4:7], v202
	ds_read_b128 v[20:23], v202 offset:32
	s_waitcnt vmcnt(15) lgkmcnt(1)
	v_mfma_f32_32x32x16_bf16 v[4:19], v[4:7], v[116:119], 0
	s_waitcnt vmcnt(14) lgkmcnt(0)
	v_mfma_f32_32x32x16_bf16 v[4:19], v[20:23], v[188:191], v[4:19]
	ds_read_b128 v[20:23], v202 offset:64
	s_waitcnt vmcnt(13) lgkmcnt(0)
	v_mfma_f32_32x32x16_bf16 v[4:19], v[20:23], v[184:187], v[4:19]
	ds_read_b128 v[20:23], v202 offset:96
	s_waitcnt vmcnt(12) lgkmcnt(0)
	v_mfma_f32_32x32x16_bf16 v[4:19], v[20:23], v[180:183], v[4:19]
	ds_read_b128 v[20:23], v202 offset:128
	s_waitcnt vmcnt(11) lgkmcnt(0)
	v_mfma_f32_32x32x16_bf16 v[4:19], v[20:23], v[176:179], v[4:19]
	ds_read_b128 v[20:23], v202 offset:160
	s_waitcnt vmcnt(10) lgkmcnt(0)
	v_mfma_f32_32x32x16_bf16 v[4:19], v[20:23], v[168:171], v[4:19]
	ds_read_b128 v[20:23], v202 offset:192
	s_waitcnt vmcnt(9) lgkmcnt(0)
	v_mfma_f32_32x32x16_bf16 v[4:19], v[20:23], v[164:167], v[4:19]
	ds_read_b128 v[20:23], v202 offset:224
	s_waitcnt vmcnt(8) lgkmcnt(0)
	v_mfma_f32_32x32x16_bf16 v[4:19], v[20:23], v[172:175], v[4:19]
	ds_read_b128 v[20:23], v202 offset:8704
	ds_read_b128 v[36:39], v202 offset:8736
	ds_read_b128 v[40:43], v202 offset:8768
	ds_read_b128 v[44:47], v202 offset:8800
	ds_read_b128 v[48:51], v202 offset:8832
	s_waitcnt lgkmcnt(4)
	v_mfma_f32_32x32x16_bf16 v[20:35], v[20:23], v[116:119], 0
	s_waitcnt lgkmcnt(3)
	v_mfma_f32_32x32x16_bf16 v[20:35], v[36:39], v[188:191], v[20:35]
	ds_read_b128 v[36:39], v202 offset:8864
	s_waitcnt lgkmcnt(3)
	v_mfma_f32_32x32x16_bf16 v[20:35], v[40:43], v[184:187], v[20:35]
	ds_read_b128 v[40:43], v202 offset:8896
	s_waitcnt lgkmcnt(3)
	v_mfma_f32_32x32x16_bf16 v[20:35], v[44:47], v[180:183], v[20:35]
	ds_read_b128 v[44:47], v202 offset:8928
	s_waitcnt lgkmcnt(3)
	v_mfma_f32_32x32x16_bf16 v[20:35], v[48:51], v[176:179], v[20:35]
	s_waitcnt lgkmcnt(2)
	v_mfma_f32_32x32x16_bf16 v[20:35], v[36:39], v[168:171], v[20:35]
	s_waitcnt lgkmcnt(1)
	v_mfma_f32_32x32x16_bf16 v[20:35], v[40:43], v[164:167], v[20:35]
	s_waitcnt lgkmcnt(0)
	v_mfma_f32_32x32x16_bf16 v[20:35], v[44:47], v[172:175], v[20:35]
	ds_read_b128 v[36:39], v202 offset:17408
	ds_read_b128 v[52:55], v202 offset:17440
	ds_read_b128 v[56:59], v202 offset:17472
	ds_read_b128 v[60:63], v202 offset:17504
	ds_read_b128 v[64:67], v202 offset:17536
	v_or_b32_e32 v214, 64, v213
	s_waitcnt lgkmcnt(4)
	v_mfma_f32_32x32x16_bf16 v[36:51], v[36:39], v[116:119], 0
	s_waitcnt lgkmcnt(3)
	v_mfma_f32_32x32x16_bf16 v[36:51], v[52:55], v[188:191], v[36:51]
	ds_read_b128 v[52:55], v202 offset:17568
	s_waitcnt lgkmcnt(3)
	v_mfma_f32_32x32x16_bf16 v[36:51], v[56:59], v[184:187], v[36:51]
	ds_read_b128 v[56:59], v202 offset:17600
	s_waitcnt lgkmcnt(3)
	v_mfma_f32_32x32x16_bf16 v[36:51], v[60:63], v[180:183], v[36:51]
	ds_read_b128 v[60:63], v202 offset:17632
	s_waitcnt lgkmcnt(3)
	v_mfma_f32_32x32x16_bf16 v[36:51], v[64:67], v[176:179], v[36:51]
	s_waitcnt lgkmcnt(2)
	v_mfma_f32_32x32x16_bf16 v[36:51], v[52:55], v[168:171], v[36:51]
	s_waitcnt lgkmcnt(1)
	v_mfma_f32_32x32x16_bf16 v[36:51], v[56:59], v[164:167], v[36:51]
	s_waitcnt lgkmcnt(0)
	v_mfma_f32_32x32x16_bf16 v[36:51], v[60:63], v[172:175], v[36:51]
	ds_read_b128 v[52:55], v202 offset:26112
	ds_read_b128 v[68:71], v202 offset:26144
	ds_read_b128 v[72:75], v202 offset:26176
	ds_read_b128 v[76:79], v202 offset:26208
	ds_read_b128 v[80:83], v202 offset:26240
	v_or_b32_e32 v212, 0x60, v213
	s_waitcnt lgkmcnt(4)
	v_mfma_f32_32x32x16_bf16 v[52:67], v[52:55], v[116:119], 0
	s_waitcnt lgkmcnt(3)
	v_mfma_f32_32x32x16_bf16 v[52:67], v[68:71], v[188:191], v[52:67]
	ds_read_b128 v[68:71], v202 offset:26272
	s_waitcnt lgkmcnt(3)
	v_mfma_f32_32x32x16_bf16 v[52:67], v[72:75], v[184:187], v[52:67]
	ds_read_b128 v[72:75], v202 offset:26304
	s_waitcnt lgkmcnt(3)
	v_mfma_f32_32x32x16_bf16 v[52:67], v[76:79], v[180:183], v[52:67]
	ds_read_b128 v[76:79], v202 offset:26336
	s_waitcnt lgkmcnt(3)
	v_mfma_f32_32x32x16_bf16 v[52:67], v[80:83], v[176:179], v[52:67]
	s_waitcnt lgkmcnt(2)
	v_mfma_f32_32x32x16_bf16 v[52:67], v[68:71], v[168:171], v[52:67]
	s_waitcnt lgkmcnt(1)
	v_mfma_f32_32x32x16_bf16 v[52:67], v[72:75], v[164:167], v[52:67]
	s_waitcnt lgkmcnt(0)
	v_mfma_f32_32x32x16_bf16 v[52:67], v[76:79], v[172:175], v[52:67]
	ds_read_b128 v[68:71], v202 offset:34816
	ds_read_b128 v[84:87], v202 offset:34848
	ds_read_b128 v[88:91], v202 offset:34880
	ds_read_b128 v[92:95], v202 offset:34912
	ds_read_b128 v[96:99], v202 offset:34944
	s_waitcnt lgkmcnt(4)
	v_mfma_f32_32x32x16_bf16 v[68:83], v[68:71], v[116:119], 0
	s_waitcnt lgkmcnt(3)
	v_mfma_f32_32x32x16_bf16 v[68:83], v[84:87], v[188:191], v[68:83]
	ds_read_b128 v[84:87], v202 offset:34976
	s_waitcnt lgkmcnt(3)
	v_mfma_f32_32x32x16_bf16 v[68:83], v[88:91], v[184:187], v[68:83]
	ds_read_b128 v[88:91], v202 offset:35008
	s_waitcnt lgkmcnt(3)
	v_mfma_f32_32x32x16_bf16 v[68:83], v[92:95], v[180:183], v[68:83]
	ds_read_b128 v[92:95], v202 offset:35040
	s_waitcnt lgkmcnt(3)
	v_mfma_f32_32x32x16_bf16 v[68:83], v[96:99], v[176:179], v[68:83]
	s_waitcnt lgkmcnt(2)
	v_mfma_f32_32x32x16_bf16 v[68:83], v[84:87], v[168:171], v[68:83]
	s_waitcnt lgkmcnt(1)
	v_mfma_f32_32x32x16_bf16 v[68:83], v[88:91], v[164:167], v[68:83]
	s_waitcnt lgkmcnt(0)
	v_mfma_f32_32x32x16_bf16 v[68:83], v[92:95], v[172:175], v[68:83]
	ds_read_b128 v[84:87], v202 offset:43520
	ds_read_b128 v[100:103], v202 offset:43552
	ds_read_b128 v[104:107], v202 offset:43584
	ds_read_b128 v[108:111], v202 offset:43616
	ds_read_b128 v[112:115], v202 offset:43648
	s_waitcnt lgkmcnt(4)
	v_mfma_f32_32x32x16_bf16 v[84:99], v[84:87], v[116:119], 0
	s_waitcnt lgkmcnt(3)
	v_mfma_f32_32x32x16_bf16 v[84:99], v[100:103], v[188:191], v[84:99]
	ds_read_b128 v[100:103], v202 offset:43680
	s_waitcnt lgkmcnt(3)
	v_mfma_f32_32x32x16_bf16 v[84:99], v[104:107], v[184:187], v[84:99]
	ds_read_b128 v[104:107], v202 offset:43712
	s_waitcnt lgkmcnt(3)
	v_mfma_f32_32x32x16_bf16 v[84:99], v[108:111], v[180:183], v[84:99]
	ds_read_b128 v[108:111], v202 offset:43744
	s_waitcnt lgkmcnt(3)
	v_mfma_f32_32x32x16_bf16 v[84:99], v[112:115], v[176:179], v[84:99]
	s_waitcnt lgkmcnt(2)
	v_mfma_f32_32x32x16_bf16 v[84:99], v[100:103], v[168:171], v[84:99]
	s_waitcnt lgkmcnt(1)
	v_mfma_f32_32x32x16_bf16 v[84:99], v[104:107], v[164:167], v[84:99]
	s_waitcnt lgkmcnt(0)
	v_mfma_f32_32x32x16_bf16 v[84:99], v[108:111], v[172:175], v[84:99]
	ds_read_b128 v[100:103], v202 offset:52224
	ds_read_b128 v[120:123], v202 offset:52256
	ds_read_b128 v[124:127], v202 offset:52288
	ds_read_b128 v[128:131], v202 offset:52320
	s_waitcnt lgkmcnt(3)
	v_mfma_f32_32x32x16_bf16 v[100:115], v[100:103], v[116:119], 0
	s_waitcnt lgkmcnt(2)
	v_mfma_f32_32x32x16_bf16 v[100:115], v[120:123], v[188:191], v[100:115]
	ds_read_b128 v[120:123], v202 offset:52352
	s_waitcnt lgkmcnt(2)
	v_mfma_f32_32x32x16_bf16 v[100:115], v[124:127], v[184:187], v[100:115]
	ds_read_b128 v[124:127], v202 offset:52384
	s_waitcnt lgkmcnt(2)
	v_mfma_f32_32x32x16_bf16 v[100:115], v[128:131], v[180:183], v[100:115]
	ds_read_b128 v[128:131], v202 offset:52416
	s_waitcnt lgkmcnt(2)
	v_mfma_f32_32x32x16_bf16 v[100:115], v[120:123], v[176:179], v[100:115]
	ds_read_b128 v[120:123], v202 offset:52448
	s_waitcnt lgkmcnt(2)
	v_mfma_f32_32x32x16_bf16 v[100:115], v[124:127], v[168:171], v[100:115]
	s_waitcnt lgkmcnt(1)
	v_mfma_f32_32x32x16_bf16 v[100:115], v[128:131], v[164:167], v[100:115]
	s_waitcnt lgkmcnt(0)
	v_mfma_f32_32x32x16_bf16 v[100:115], v[120:123], v[172:175], v[100:115]
	ds_read_b128 v[120:123], v202 offset:60928
	ds_read_b128 v[204:207], v202 offset:60960
	s_waitcnt lgkmcnt(1)
	v_mfma_f32_32x32x16_bf16 v[116:131], v[120:123], v[116:119], 0
	s_waitcnt lgkmcnt(0)
	v_mfma_f32_32x32x16_bf16 v[116:131], v[204:207], v[188:191], v[116:131]
	ds_read_b128 v[188:191], v202 offset:60992
	s_waitcnt lgkmcnt(0)
	v_mfma_f32_32x32x16_bf16 v[116:131], v[188:191], v[184:187], v[116:131]
	ds_read_b128 v[184:187], v202 offset:61024
	s_waitcnt lgkmcnt(0)
	v_mfma_f32_32x32x16_bf16 v[116:131], v[184:187], v[180:183], v[116:131]
	ds_read_b128 v[180:183], v202 offset:61056
	s_waitcnt lgkmcnt(0)
	v_mfma_f32_32x32x16_bf16 v[116:131], v[180:183], v[176:179], v[116:131]
	ds_read_b128 v[176:179], v202 offset:61088
	s_waitcnt lgkmcnt(0)
	v_mfma_f32_32x32x16_bf16 v[116:131], v[176:179], v[168:171], v[116:131]
	ds_read_b128 v[168:171], v202 offset:61120
	s_waitcnt lgkmcnt(0)
	v_mfma_f32_32x32x16_bf16 v[116:131], v[168:171], v[164:167], v[116:131]
	ds_read_b128 v[164:167], v202 offset:61152
	s_waitcnt lgkmcnt(0)
	v_mfma_f32_32x32x16_bf16 v[116:131], v[164:167], v[172:175], v[116:131]
	v_max3_f32 v164, v4, s76, v5
	v_max3_f32 v164, v164, v6, v7
	v_max3_f32 v164, v164, v8, v9
	v_max3_f32 v164, v164, v10, v11
	v_max3_f32 v164, v164, v12, v13
	v_max3_f32 v164, v164, v14, v15
	v_max3_f32 v164, v164, v16, v17
	v_max3_f32 v164, v164, v18, v19
	v_max3_f32 v164, v164, v20, v21
	v_max3_f32 v164, v164, v22, v23
	v_max3_f32 v164, v164, v24, v25
	v_max3_f32 v164, v164, v26, v27
	v_max3_f32 v164, v164, v28, v29
	v_max3_f32 v164, v164, v30, v31
	v_max3_f32 v164, v164, v32, v33
	v_max3_f32 v164, v164, v34, v35
	v_max3_f32 v164, v164, v36, v37
	v_max3_f32 v164, v164, v38, v39
	v_max3_f32 v164, v164, v40, v41
	v_max3_f32 v164, v164, v42, v43
	v_max3_f32 v164, v164, v44, v45
	v_max3_f32 v164, v164, v46, v47
	v_max3_f32 v164, v164, v48, v49
	v_max3_f32 v164, v164, v50, v51
	v_max3_f32 v164, v164, v52, v53
	v_max3_f32 v164, v164, v54, v55
	v_max3_f32 v164, v164, v56, v57
	v_max3_f32 v164, v164, v58, v59
	v_max3_f32 v164, v164, v60, v61
	v_max3_f32 v164, v164, v62, v63
	v_max3_f32 v164, v164, v64, v65
	v_max3_f32 v164, v164, v66, v67
	v_max3_f32 v164, v164, v68, v69
	v_max3_f32 v164, v164, v70, v71
	v_max3_f32 v164, v164, v72, v73
	v_max3_f32 v164, v164, v74, v75
	v_max3_f32 v164, v164, v76, v77
	v_max3_f32 v164, v164, v78, v79
	v_max3_f32 v164, v164, v80, v81
	v_max3_f32 v164, v164, v82, v83
	v_max3_f32 v164, v164, v84, v85
	v_max3_f32 v164, v164, v86, v87
	v_max3_f32 v164, v164, v88, v89
	v_max3_f32 v164, v164, v90, v91
	v_max3_f32 v164, v164, v92, v93
	v_max3_f32 v164, v164, v94, v95
	v_max3_f32 v164, v164, v96, v97
	v_max3_f32 v164, v164, v98, v99
	v_max3_f32 v164, v164, v100, v101
	v_max3_f32 v164, v164, v102, v103
	v_max3_f32 v164, v164, v104, v105
	v_max3_f32 v164, v164, v106, v107
	v_max3_f32 v164, v164, v108, v109
	v_max3_f32 v164, v164, v110, v111
	v_max3_f32 v164, v164, v112, v113
	v_max3_f32 v164, v164, v114, v115
	v_max3_f32 v164, v164, v116, v117
	v_max3_f32 v164, v164, v118, v119
	v_max3_f32 v164, v164, v120, v121
	v_max3_f32 v164, v164, v122, v123
	v_max3_f32 v164, v164, v124, v125
	v_max3_f32 v164, v164, v126, v127
	v_cmp_lt_i32_e32 vcc, v236, v235
	v_max3_f32 v164, v164, v128, v129
	v_max3_f32 v164, v164, v130, v131
	v_cndmask_b32_e32 v165, v231, v236, vcc
	v_lshlrev_b32_e32 v216, 2, v165
	ds_bpermute_b32 v165, v216, v164
	s_waitcnt lgkmcnt(0)
	s_barrier
	v_max_f32_e32 v165, v165, v165
	v_max_f32_e32 v217, v164, v165
	v_sub_f32_e32 v10, v10, v217
	v_exp_f32_e32 v164, v10
	v_sub_f32_e32 v10, v11, v217
	v_exp_f32_e32 v165, v10
	v_sub_f32_e32 v10, v12, v217
	v_exp_f32_e32 v166, v10
	v_sub_f32_e32 v10, v13, v217
	v_exp_f32_e32 v167, v10
	v_sub_f32_e32 v10, v14, v217
	v_exp_f32_e32 v168, v10
	v_sub_f32_e32 v10, v15, v217
	v_exp_f32_e32 v169, v10
	v_sub_f32_e32 v10, v16, v217
	v_exp_f32_e32 v170, v10
	v_sub_f32_e32 v10, v17, v217
	v_sub_f32_e32 v16, v26, v217
	v_exp_f32_e32 v171, v10
	v_sub_f32_e32 v10, v18, v217
	v_exp_f32_e32 v18, v16
	v_sub_f32_e32 v16, v27, v217
	v_exp_f32_e32 v172, v10
	v_sub_f32_e32 v10, v19, v217
	v_exp_f32_e32 v19, v16
	v_sub_f32_e32 v16, v28, v217
	v_exp_f32_e32 v28, v16
	v_sub_f32_e32 v16, v29, v217
	v_exp_f32_e32 v29, v16
	v_sub_f32_e32 v16, v30, v217
	v_exp_f32_e32 v30, v16
	v_sub_f32_e32 v16, v31, v217
	v_exp_f32_e32 v31, v16
	v_sub_f32_e32 v16, v32, v217
	v_exp_f32_e32 v32, v16
	v_sub_f32_e32 v16, v33, v217
	v_exp_f32_e32 v33, v16
	v_sub_f32_e32 v16, v34, v217
	v_exp_f32_e32 v173, v10
	v_sub_f32_e32 v10, v20, v217
	v_exp_f32_e32 v34, v16
	v_sub_f32_e32 v16, v35, v217
	v_sub_f32_e32 v20, v38, v217
	v_exp_f32_e32 v35, v16
	v_sub_f32_e32 v16, v36, v217
	v_exp_f32_e32 v36, v20
	v_sub_f32_e32 v20, v39, v217
	v_sub_f32_e32 v17, v37, v217
	v_exp_f32_e32 v37, v20
	v_sub_f32_e32 v20, v40, v217
	v_exp_f32_e32 v38, v20
	v_sub_f32_e32 v20, v41, v217
	v_exp_f32_e32 v39, v20
	v_sub_f32_e32 v20, v42, v217
	v_exp_f32_e32 v40, v20
	v_sub_f32_e32 v20, v43, v217
	v_exp_f32_e32 v41, v20
	v_sub_f32_e32 v20, v44, v217
	v_exp_f32_e32 v42, v20
	v_sub_f32_e32 v20, v45, v217
	v_exp_f32_e32 v43, v20
	v_sub_f32_e32 v20, v46, v217
	v_exp_f32_e32 v174, v20
	v_sub_f32_e32 v20, v47, v217
	v_exp_f32_e32 v175, v20
	v_sub_f32_e32 v20, v48, v217
	v_exp_f32_e32 v176, v20
	v_sub_f32_e32 v20, v49, v217
	v_exp_f32_e32 v177, v20
	v_sub_f32_e32 v20, v50, v217
	v_exp_f32_e32 v178, v20
	v_sub_f32_e32 v20, v51, v217
	v_exp_f32_e32 v179, v20
	v_sub_f32_e32 v20, v52, v217
	v_exp_f32_e32 v44, v20
	v_sub_f32_e32 v20, v53, v217
	v_exp_f32_e32 v45, v20
	v_sub_f32_e32 v20, v54, v217
	v_exp_f32_e32 v46, v20
	v_sub_f32_e32 v20, v55, v217
	v_exp_f32_e32 v47, v20
	v_sub_f32_e32 v20, v56, v217
	v_exp_f32_e32 v48, v20
	v_sub_f32_e32 v20, v57, v217
	v_exp_f32_e32 v49, v20
	v_sub_f32_e32 v20, v58, v217
	v_exp_f32_e32 v50, v20
	v_sub_f32_e32 v20, v59, v217
	v_exp_f32_e32 v51, v20
	v_sub_f32_e32 v20, v60, v217
	v_exp_f32_e32 v56, v20
	v_sub_f32_e32 v20, v61, v217
	v_exp_f32_e32 v57, v20
	v_sub_f32_e32 v20, v62, v217
	v_exp_f32_e32 v60, v20
	v_sub_f32_e32 v20, v63, v217
	v_exp_f32_e32 v61, v20
	v_sub_f32_e32 v20, v64, v217
	v_exp_f32_e32 v180, v20
	v_sub_f32_e32 v20, v65, v217
	v_exp_f32_e32 v181, v20
	v_sub_f32_e32 v20, v66, v217
	v_exp_f32_e32 v182, v20
	v_sub_f32_e32 v20, v67, v217
	v_exp_f32_e32 v183, v20
	v_sub_f32_e32 v20, v68, v217
	v_exp_f32_e32 v52, v20
	v_sub_f32_e32 v20, v69, v217
	v_exp_f32_e32 v53, v20
	v_sub_f32_e32 v20, v70, v217
	v_exp_f32_e32 v54, v20
	v_sub_f32_e32 v20, v71, v217
	v_exp_f32_e32 v55, v20
	v_sub_f32_e32 v20, v72, v217
	v_exp_f32_e32 v58, v20
	v_sub_f32_e32 v20, v73, v217
	v_exp_f32_e32 v59, v20
	v_sub_f32_e32 v20, v74, v217
	v_exp_f32_e32 v64, v20
	v_sub_f32_e32 v20, v75, v217
	v_exp_f32_e32 v65, v20
	v_sub_f32_e32 v20, v76, v217
	v_exp_f32_e32 v68, v20
	v_sub_f32_e32 v20, v77, v217
	v_exp_f32_e32 v69, v20
	v_sub_f32_e32 v20, v78, v217
	v_exp_f32_e32 v72, v20
	v_sub_f32_e32 v20, v79, v217
	v_exp_f32_e32 v73, v20
	v_sub_f32_e32 v20, v80, v217
	v_exp_f32_e32 v186, v20
	v_sub_f32_e32 v20, v81, v217
	v_exp_f32_e32 v187, v20
	v_sub_f32_e32 v20, v82, v217
	v_exp_f32_e32 v190, v20
	v_sub_f32_e32 v20, v83, v217
	v_exp_f32_e32 v191, v20
	v_sub_f32_e32 v20, v84, v217
	v_exp_f32_e32 v62, v20
	v_sub_f32_e32 v20, v85, v217
	v_exp_f32_e32 v63, v20
	v_sub_f32_e32 v20, v86, v217
	v_exp_f32_e32 v66, v20
	v_sub_f32_e32 v20, v87, v217
	v_exp_f32_e32 v67, v20
	v_sub_f32_e32 v20, v88, v217
	v_exp_f32_e32 v70, v20
	v_sub_f32_e32 v20, v89, v217
	v_exp_f32_e32 v71, v20
	v_sub_f32_e32 v20, v90, v217
	v_exp_f32_e32 v184, v20
	v_sub_f32_e32 v20, v91, v217
	v_exp_f32_e32 v185, v20
	v_sub_f32_e32 v20, v92, v217
	v_exp_f32_e32 v188, v20
	v_sub_f32_e32 v20, v93, v217
	v_exp_f32_e32 v189, v20
	v_sub_f32_e32 v20, v94, v217
	v_exp_f32_e32 v202, v20
	v_sub_f32_e32 v20, v95, v217
	v_exp_f32_e32 v203, v20
	v_sub_f32_e32 v20, v96, v217
	v_exp_f32_e32 v204, v20
	v_sub_f32_e32 v20, v97, v217
	v_exp_f32_e32 v205, v20
	v_sub_f32_e32 v20, v98, v217
	v_exp_f32_e32 v206, v20
	v_sub_f32_e32 v20, v99, v217
	v_exp_f32_e32 v207, v20
	v_sub_f32_e32 v20, v100, v217
	v_exp_f32_e32 v74, v20
	v_sub_f32_e32 v20, v101, v217
	v_exp_f32_e32 v75, v20
	v_sub_f32_e32 v20, v102, v217
	v_exp_f32_e32 v92, v20
	v_sub_f32_e32 v20, v103, v217
	v_exp_f32_e32 v93, v20
	v_sub_f32_e32 v20, v104, v217
	v_exp_f32_e32 v94, v20
	v_sub_f32_e32 v20, v105, v217
	v_exp_f32_e32 v95, v20
	v_sub_f32_e32 v20, v106, v217
	v_exp_f32_e32 v96, v20
	v_sub_f32_e32 v20, v107, v217
	v_exp_f32_e32 v97, v20
	v_sub_f32_e32 v20, v108, v217
	v_exp_f32_e32 v98, v20
	v_sub_f32_e32 v20, v109, v217
	v_exp_f32_e32 v99, v20
	v_sub_f32_e32 v20, v110, v217
	v_exp_f32_e32 v100, v20
	v_sub_f32_e32 v20, v111, v217
	v_exp_f32_e32 v101, v20
	v_sub_f32_e32 v20, v112, v217
	v_exp_f32_e32 v102, v20
	v_sub_f32_e32 v20, v113, v217
	v_exp_f32_e32 v103, v20
	v_sub_f32_e32 v20, v114, v217
	v_exp_f32_e32 v104, v20
	v_sub_f32_e32 v20, v115, v217
	v_exp_f32_e32 v105, v20
	v_sub_f32_e32 v20, v116, v217
	v_exp_f32_e32 v76, v20
	v_sub_f32_e32 v20, v117, v217
	v_exp_f32_e32 v77, v20
	v_sub_f32_e32 v20, v118, v217
	v_exp_f32_e32 v80, v20
	v_sub_f32_e32 v20, v119, v217
	v_exp_f32_e32 v81, v20
	v_sub_f32_e32 v20, v120, v217
	v_exp_f32_e32 v84, v20
	v_sub_f32_e32 v20, v121, v217
	v_exp_f32_e32 v85, v20
	v_sub_f32_e32 v20, v122, v217
	v_exp_f32_e32 v88, v20
	v_sub_f32_e32 v20, v123, v217
	v_exp_f32_e32 v89, v20
	v_sub_f32_e32 v20, v124, v217
	v_exp_f32_e32 v78, v20
	v_sub_f32_e32 v20, v125, v217
	v_exp_f32_e32 v79, v20
	v_sub_f32_e32 v20, v126, v217
	v_sub_f32_e32 v4, v4, v217
	v_exp_f32_e32 v82, v20
	v_sub_f32_e32 v20, v127, v217
	v_sub_f32_e32 v5, v5, v217
	v_exp_f32_e32 v4, v4
	v_exp_f32_e32 v83, v20
	v_sub_f32_e32 v20, v128, v217
	v_exp_f32_e32 v5, v5
	v_sub_f32_e32 v6, v6, v217
	v_exp_f32_e32 v86, v20
	v_sub_f32_e32 v20, v129, v217
	v_exp_f32_e32 v6, v6
	v_sub_f32_e32 v7, v7, v217
	v_exp_f32_e32 v87, v20
	v_sub_f32_e32 v20, v130, v217
	v_exp_f32_e32 v7, v7
	v_sub_f32_e32 v8, v8, v217
	v_exp_f32_e32 v90, v20
	v_sub_f32_e32 v20, v131, v217
	v_exp_f32_e32 v8, v8
	v_sub_f32_e32 v9, v9, v217
	v_exp_f32_e32 v91, v20
	v_add_f32_e32 v20, 0, v4
	v_exp_f32_e32 v9, v9
	v_add_f32_e32 v20, v5, v20
	v_add_f32_e32 v20, v6, v20
	v_add_f32_e32 v20, v7, v20
	v_add_f32_e32 v20, v8, v20
	v_add_f32_e32 v20, v9, v20
	v_add_f32_e32 v20, v164, v20
	v_add_f32_e32 v20, v165, v20
	v_add_f32_e32 v20, v166, v20
	v_add_f32_e32 v20, v167, v20
	v_add_f32_e32 v20, v168, v20
	v_add_f32_e32 v20, v169, v20
	v_exp_f32_e32 v10, v10
	v_sub_f32_e32 v11, v21, v217
	v_add_f32_e32 v20, v170, v20
	v_exp_f32_e32 v11, v11
	v_sub_f32_e32 v12, v22, v217
	v_add_f32_e32 v20, v171, v20
	v_exp_f32_e32 v12, v12
	v_sub_f32_e32 v13, v23, v217
	v_add_f32_e32 v20, v172, v20
	v_exp_f32_e32 v13, v13
	v_sub_f32_e32 v14, v24, v217
	v_add_f32_e32 v20, v173, v20
	v_exp_f32_e32 v14, v14
	v_sub_f32_e32 v15, v25, v217
	v_add_f32_e32 v20, v10, v20
	v_exp_f32_e32 v15, v15
	v_add_f32_e32 v20, v11, v20
	v_add_f32_e32 v20, v12, v20
	v_add_f32_e32 v20, v13, v20
	v_add_f32_e32 v20, v14, v20
	v_add_f32_e32 v20, v15, v20
	v_add_f32_e32 v20, v18, v20
	v_add_f32_e32 v20, v19, v20
	v_add_f32_e32 v20, v28, v20
	v_add_f32_e32 v20, v29, v20
	v_add_f32_e32 v20, v30, v20
	v_add_f32_e32 v20, v31, v20
	v_exp_f32_e32 v16, v16
	v_add_f32_e32 v20, v32, v20
	v_exp_f32_e32 v17, v17
	v_add_f32_e32 v20, v33, v20
	v_add_f32_e32 v20, v34, v20
	v_add_f32_e32 v20, v35, v20
	v_add_f32_e32 v20, v16, v20
	v_add_f32_e32 v20, v17, v20
	v_add_f32_e32 v20, v36, v20
	v_add_f32_e32 v20, v37, v20
	v_add_f32_e32 v20, v38, v20
	v_add_f32_e32 v20, v39, v20
	v_add_f32_e32 v20, v40, v20
	v_add_f32_e32 v20, v41, v20
	v_add_f32_e32 v20, v42, v20
	v_add_f32_e32 v20, v43, v20
	v_add_f32_e32 v20, v174, v20
	v_add_f32_e32 v20, v175, v20
	v_add_f32_e32 v20, v176, v20
	v_add_f32_e32 v20, v177, v20
	v_add_f32_e32 v20, v178, v20
	v_add_f32_e32 v20, v179, v20
	v_add_f32_e32 v20, v44, v20
	v_add_f32_e32 v20, v45, v20
	v_add_f32_e32 v20, v46, v20
	v_add_f32_e32 v20, v47, v20
	v_add_f32_e32 v20, v48, v20
	v_add_f32_e32 v20, v49, v20
	v_add_f32_e32 v20, v50, v20
	v_add_f32_e32 v20, v51, v20
	v_add_f32_e32 v20, v56, v20
	v_add_f32_e32 v20, v57, v20
	v_add_f32_e32 v20, v60, v20
	v_add_f32_e32 v20, v61, v20
	v_add_f32_e32 v20, v180, v20
	v_add_f32_e32 v20, v181, v20
	v_add_f32_e32 v20, v182, v20
	v_add_f32_e32 v20, v183, v20
	v_add_f32_e32 v20, v52, v20
	v_add_f32_e32 v20, v53, v20
	v_add_f32_e32 v20, v54, v20
	v_add_f32_e32 v20, v55, v20
	v_add_f32_e32 v20, v58, v20
	v_add_f32_e32 v20, v59, v20
	v_add_f32_e32 v20, v64, v20
	v_add_f32_e32 v20, v65, v20
	v_add_f32_e32 v20, v68, v20
	v_add_f32_e32 v20, v69, v20
	v_add_f32_e32 v20, v72, v20
	v_add_f32_e32 v20, v73, v20
	v_add_f32_e32 v20, v186, v20
	v_add_f32_e32 v20, v187, v20
	v_add_f32_e32 v20, v190, v20
	v_add_f32_e32 v20, v191, v20
	v_add_f32_e32 v20, v62, v20
	v_add_f32_e32 v20, v63, v20
	v_add_f32_e32 v20, v66, v20
	v_add_f32_e32 v20, v67, v20
	v_add_f32_e32 v20, v70, v20
	v_add_f32_e32 v20, v71, v20
	v_add_f32_e32 v20, v184, v20
	v_add_f32_e32 v20, v185, v20
	v_add_f32_e32 v20, v188, v20
	v_add_f32_e32 v20, v189, v20
	v_add_f32_e32 v20, v202, v20
	v_add_f32_e32 v20, v203, v20
	v_add_f32_e32 v20, v204, v20
	v_add_f32_e32 v20, v205, v20
	v_add_f32_e32 v20, v206, v20
	v_add_f32_e32 v20, v207, v20
	v_add_f32_e32 v20, v74, v20
	v_add_f32_e32 v20, v75, v20
	v_add_f32_e32 v20, v92, v20
	v_add_f32_e32 v20, v93, v20
	v_add_f32_e32 v20, v94, v20
	v_add_f32_e32 v20, v95, v20
	v_add_f32_e32 v20, v96, v20
	v_add_f32_e32 v20, v97, v20
	v_add_f32_e32 v20, v98, v20
	v_add_f32_e32 v20, v99, v20
	v_add_f32_e32 v20, v100, v20
	v_add_f32_e32 v20, v101, v20
	v_add_f32_e32 v20, v102, v20
	v_add_f32_e32 v20, v103, v20
	v_add_f32_e32 v20, v104, v20
	v_add_f32_e32 v20, v105, v20
	v_add_f32_e32 v20, v76, v20
	v_add_f32_e32 v20, v77, v20
	v_add_f32_e32 v20, v80, v20
	v_add_f32_e32 v20, v81, v20
	v_add_f32_e32 v20, v84, v20
	v_add_f32_e32 v20, v85, v20
	v_add_f32_e32 v20, v88, v20
	v_add_f32_e32 v20, v89, v20
	v_add_f32_e32 v20, v78, v20
	v_add_f32_e32 v20, v79, v20
	v_add_f32_e32 v20, v82, v20
	v_add_f32_e32 v20, v83, v20
	v_add_f32_e32 v20, v86, v20
	v_add_f32_e32 v20, v87, v20
	v_add_f32_e32 v20, v90, v20
	v_add_f32_e32 v20, v91, v20
	ds_bpermute_b32 v21, v216, v20
	s_waitcnt lgkmcnt(0)
	v_add_f32_e32 v20, v20, v21
	v_div_scale_f32 v21, s[42:43], v20, v20, 1.0
	v_rcp_f32_e32 v22, v21
	s_nop 0
	v_fma_f32 v23, -v21, v22, 1.0
	v_fmac_f32_e32 v22, v23, v22
	v_div_scale_f32 v23, vcc, 1.0, v20, 1.0
	v_mul_f32_e32 v24, v23, v22
	v_fma_f32 v25, -v21, v24, v23
	v_fmac_f32_e32 v24, v25, v22
	v_fma_f32 v21, -v21, v24, v23
	v_div_fmas_f32 v21, v21, v22, v24
	v_div_fixup_f32 v106, v21, v20, 1.0
	v_pk_mul_f32 v[6:7], v[6:7], v[106:107] op_sel_hi:[1,0]
	v_pk_mul_f32 v[4:5], v[4:5], v[106:107] op_sel_hi:[1,0]
	v_pk_mul_f32 v[8:9], v[8:9], v[106:107] op_sel_hi:[1,0]
	v_cvt_pk_bf16_f32 v21, v6, v7
	v_pk_mul_f32 v[6:7], v[12:13], v[106:107] op_sel_hi:[1,0]
	v_pk_mul_f32 v[24:25], v[164:165], v[106:107] op_sel_hi:[1,0]
	v_pk_mul_f32 v[108:109], v[168:169], v[106:107] op_sel_hi:[1,0]
	v_cvt_pk_bf16_f32 v20, v4, v5
	v_cvt_pk_bf16_f32 v22, v8, v9
	v_pk_mul_f32 v[4:5], v[10:11], v[106:107] op_sel_hi:[1,0]
	v_pk_mul_f32 v[8:9], v[14:15], v[106:107] op_sel_hi:[1,0]
	v_pk_mul_f32 v[10:11], v[18:19], v[106:107] op_sel_hi:[1,0]
	v_pk_mul_f32 v[18:19], v[32:33], v[106:107] op_sel_hi:[1,0]
	v_cvt_pk_bf16_f32 v33, v6, v7
	v_pk_mul_f32 v[6:7], v[36:37], v[106:107] op_sel_hi:[1,0]
	v_cvt_pk_bf16_f32 v23, v24, v25
	v_cvt_pk_bf16_f32 v25, v108, v109
	v_pk_mul_f32 v[108:109], v[34:35], v[106:107] op_sel_hi:[1,0]
	v_cvt_pk_bf16_f32 v32, v4, v5
	v_cvt_pk_bf16_f32 v34, v8, v9
	v_pk_mul_f32 v[4:5], v[16:17], v[106:107] op_sel_hi:[1,0]
	v_pk_mul_f32 v[8:9], v[38:39], v[106:107] op_sel_hi:[1,0]
	v_cvt_pk_bf16_f32 v37, v6, v7
	v_pk_mul_f32 v[6:7], v[46:47], v[106:107] op_sel_hi:[1,0]
	v_cvt_pk_bf16_f32 v35, v10, v11
	v_pk_mul_f32 v[10:11], v[40:41], v[106:107] op_sel_hi:[1,0]
	v_cvt_pk_bf16_f32 v36, v4, v5
	v_cvt_pk_bf16_f32 v38, v8, v9
	v_pk_mul_f32 v[4:5], v[44:45], v[106:107] op_sel_hi:[1,0]
	v_pk_mul_f32 v[8:9], v[48:49], v[106:107] op_sel_hi:[1,0]
	v_cvt_pk_bf16_f32 v49, v6, v7
	v_pk_mul_f32 v[6:7], v[54:55], v[106:107] op_sel_hi:[1,0]
	v_pk_mul_f32 v[12:13], v[28:29], v[106:107] op_sel_hi:[1,0]
	v_cvt_pk_bf16_f32 v39, v10, v11
	v_pk_mul_f32 v[10:11], v[50:51], v[106:107] op_sel_hi:[1,0]
	v_cvt_pk_bf16_f32 v48, v4, v5
	v_pk_mul_f32 v[4:5], v[52:53], v[106:107] op_sel_hi:[1,0]
	v_cvt_pk_bf16_f32 v53, v6, v7
	v_pk_mul_f32 v[6:7], v[66:67], v[106:107] op_sel_hi:[1,0]
	v_cvt_pk_bf16_f32 v28, v12, v13
	v_pk_mul_f32 v[12:13], v[42:43], v[106:107] op_sel_hi:[1,0]
	v_cvt_pk_bf16_f32 v51, v10, v11
	v_pk_mul_f32 v[10:11], v[64:65], v[106:107] op_sel_hi:[1,0]
	v_cvt_pk_bf16_f32 v52, v4, v5
	v_pk_mul_f32 v[4:5], v[62:63], v[106:107] op_sel_hi:[1,0]
	v_cvt_pk_bf16_f32 v65, v6, v7
	v_pk_mul_f32 v[6:7], v[92:93], v[106:107] op_sel_hi:[1,0]
	v_add_u32_e32 v92, s11, v215
	v_pk_mul_f32 v[14:15], v[30:31], v[106:107] op_sel_hi:[1,0]
	v_cvt_pk_bf16_f32 v40, v12, v13
	v_pk_mul_f32 v[12:13], v[56:57], v[106:107] op_sel_hi:[1,0]
	v_cvt_pk_bf16_f32 v64, v4, v5
	v_pk_mul_f32 v[4:5], v[74:75], v[106:107] op_sel_hi:[1,0]
	v_mad_u32_u24 v93, v213, s8, v92
	v_cvt_pk_bf16_f32 v29, v14, v15
	v_cvt_pk_bf16_f32 v30, v18, v19
	v_pk_mul_f32 v[14:15], v[174:175], v[106:107] op_sel_hi:[1,0]
	v_pk_mul_f32 v[16:17], v[176:177], v[106:107] op_sel_hi:[1,0]
	v_pk_mul_f32 v[18:19], v[178:179], v[106:107] op_sel_hi:[1,0]
	v_cvt_pk_bf16_f32 v44, v12, v13
	v_pk_mul_f32 v[12:13], v[68:69], v[106:107] op_sel_hi:[1,0]
	v_cvt_pk_bf16_f32 v68, v4, v5
	v_cvt_pk_bf16_f32 v69, v6, v7
	ds_read2_b64 v[4:7], v93 offset1:2
	v_cvt_pk_bf16_f32 v41, v14, v15
	v_cvt_pk_bf16_f32 v42, v16, v17
	v_cvt_pk_bf16_f32 v43, v18, v19
	v_pk_mul_f32 v[14:15], v[60:61], v[106:107] op_sel_hi:[1,0]
	v_pk_mul_f32 v[16:17], v[180:181], v[106:107] op_sel_hi:[1,0]
	v_pk_mul_f32 v[18:19], v[182:183], v[106:107] op_sel_hi:[1,0]
	v_cvt_pk_bf16_f32 v50, v8, v9
	v_cvt_pk_bf16_f32 v45, v14, v15
	v_cvt_pk_bf16_f32 v46, v16, v17
	v_cvt_pk_bf16_f32 v47, v18, v19
	v_pk_mul_f32 v[8:9], v[58:59], v[106:107] op_sel_hi:[1,0]
	v_pk_mul_f32 v[14:15], v[72:73], v[106:107] op_sel_hi:[1,0]
	v_pk_mul_f32 v[16:17], v[186:187], v[106:107] op_sel_hi:[1,0]
	v_pk_mul_f32 v[18:19], v[190:191], v[106:107] op_sel_hi:[1,0]
	v_cvt_pk_bf16_f32 v54, v8, v9
	v_cvt_pk_bf16_f32 v55, v10, v11
	v_cvt_pk_bf16_f32 v56, v12, v13
	v_cvt_pk_bf16_f32 v57, v14, v15
	v_cvt_pk_bf16_f32 v58, v16, v17
	v_cvt_pk_bf16_f32 v59, v18, v19
	v_pk_mul_f32 v[8:9], v[70:71], v[106:107] op_sel_hi:[1,0]
	v_pk_mul_f32 v[10:11], v[184:185], v[106:107] op_sel_hi:[1,0]
	v_pk_mul_f32 v[12:13], v[188:189], v[106:107] op_sel_hi:[1,0]
	v_pk_mul_f32 v[14:15], v[202:203], v[106:107] op_sel_hi:[1,0]
	v_pk_mul_f32 v[16:17], v[204:205], v[106:107] op_sel_hi:[1,0]
	v_pk_mul_f32 v[18:19], v[206:207], v[106:107] op_sel_hi:[1,0]
	v_cvt_pk_bf16_f32 v66, v8, v9
	v_cvt_pk_bf16_f32 v67, v10, v11
	v_cvt_pk_bf16_f32 v60, v12, v13
	v_cvt_pk_bf16_f32 v61, v14, v15
	v_cvt_pk_bf16_f32 v62, v16, v17
	v_cvt_pk_bf16_f32 v63, v18, v19
	v_pk_mul_f32 v[8:9], v[94:95], v[106:107] op_sel_hi:[1,0]
	v_pk_mul_f32 v[10:11], v[96:97], v[106:107] op_sel_hi:[1,0]
	v_pk_mul_f32 v[12:13], v[98:99], v[106:107] op_sel_hi:[1,0]
	v_pk_mul_f32 v[14:15], v[100:101], v[106:107] op_sel_hi:[1,0]
	v_pk_mul_f32 v[16:17], v[102:103], v[106:107] op_sel_hi:[1,0]
	v_pk_mul_f32 v[18:19], v[104:105], v[106:107] op_sel_hi:[1,0]
	v_cvt_pk_bf16_f32 v70, v8, v9
	v_cvt_pk_bf16_f32 v71, v10, v11
	v_cvt_pk_bf16_f32 v72, v12, v13
	v_cvt_pk_bf16_f32 v73, v14, v15
	v_cvt_pk_bf16_f32 v74, v16, v17
	v_cvt_pk_bf16_f32 v75, v18, v19
	s_waitcnt lgkmcnt(0)
	v_mfma_f32_32x32x16_bf16 v[4:19], v[20:23], v[4:7], 0
	v_mul_f32_e64 v26, v166, v106
	v_mul_f32_e64 v27, v167, v106
	v_mul_f32_e64 v110, v170, v106
	v_mul_f32_e64 v111, v171, v106
	v_mul_f32_e64 v112, v172, v106
	v_mul_f32_e64 v113, v173, v106
	v_cvt_pk_bf16_f32 v24, v26, v27
	v_cvt_pk_bf16_f32 v26, v110, v111
	v_cvt_pk_bf16_f32 v27, v112, v113
	v_pk_mul_f32 v[94:95], v[80:81], v[106:107] op_sel_hi:[1,0]
	v_pk_mul_f32 v[96:97], v[78:79], v[106:107] op_sel_hi:[1,0]
	ds_read2_b64 v[78:81], v93 offset0:4 offset1:6
	s_waitcnt lgkmcnt(0)
	v_mfma_f32_32x32x16_bf16 v[4:19], v[24:27], v[78:81], v[4:19]
	v_mul_f32_e64 v84, v84, v106
	v_mul_f32_e64 v85, v85, v106
	v_mul_f32_e64 v98, v86, v106
	v_mul_f32_e64 v99, v87, v106
	v_cvt_pk_bf16_f32 v78, v84, v85
	ds_read2_b64 v[84:87], v93 offset0:8 offset1:10
	v_pk_mul_f32 v[88:89], v[88:89], v[106:107] op_sel_hi:[1,0]
	v_cvt_pk_bf16_f32 v31, v108, v109
	v_cvt_pk_bf16_f32 v79, v88, v89
	s_waitcnt lgkmcnt(0)
	v_mfma_f32_32x32x16_bf16 v[4:19], v[32:35], v[84:87], v[4:19]
	ds_read2_b64 v[86:89], v93 offset0:12 offset1:14
	v_lshrrev_b32_e32 v84, 3, v211
	v_and_b32_e32 v84, 4, v84
	v_lshlrev_b32_e32 v85, 1, v211
	v_mul_f32_e64 v76, v76, v106
	v_mul_f32_e64 v77, v77, v106
	v_pk_mul_f32 v[82:83], v[82:83], v[106:107] op_sel_hi:[1,0]
	v_pk_mul_f32 v[90:91], v[90:91], v[106:107] op_sel_hi:[1,0]
	v_mul_u32_u24_e32 v84, 0x110, v84
	v_and_b32_e32 v85, 62, v85
	v_cvt_pk_bf16_f32 v76, v76, v77
	v_cvt_pk_bf16_f32 v77, v94, v95
	v_cvt_pk_bf16_f32 v80, v96, v97
	v_cvt_pk_bf16_f32 v81, v82, v83
	v_cvt_pk_bf16_f32 v82, v98, v99
	v_cvt_pk_bf16_f32 v83, v90, v91
	v_add3_u32 v84, s4, v84, v85
	s_waitcnt lgkmcnt(0)
	v_mfma_f32_32x32x16_bf16 v[4:19], v[28:31], v[86:89], v[4:19]
	ds_read2_b64 v[86:89], v93 offset0:16 offset1:18
	s_waitcnt lgkmcnt(0)
	v_mfma_f32_32x32x16_bf16 v[4:19], v[36:39], v[86:89], v[4:19]
	ds_read2_b64 v[86:89], v93 offset0:20 offset1:22
	s_waitcnt lgkmcnt(0)
	v_mfma_f32_32x32x16_bf16 v[4:19], v[40:43], v[86:89], v[4:19]
	ds_read2_b64 v[86:89], v93 offset0:24 offset1:26
	s_waitcnt lgkmcnt(0)
	v_mfma_f32_32x32x16_bf16 v[4:19], v[48:51], v[86:89], v[4:19]
	ds_read2_b64 v[86:89], v93 offset0:28 offset1:30
	s_waitcnt lgkmcnt(0)
	v_mfma_f32_32x32x16_bf16 v[4:19], v[44:47], v[86:89], v[4:19]
	ds_read2_b64 v[86:89], v93 offset0:32 offset1:34
	s_waitcnt lgkmcnt(0)
	v_mfma_f32_32x32x16_bf16 v[4:19], v[52:55], v[86:89], v[4:19]
	ds_read2_b64 v[86:89], v93 offset0:36 offset1:38
	s_waitcnt lgkmcnt(0)
	v_mfma_f32_32x32x16_bf16 v[4:19], v[56:59], v[86:89], v[4:19]
	ds_read2_b64 v[86:89], v93 offset0:40 offset1:42
	s_waitcnt lgkmcnt(0)
	v_mfma_f32_32x32x16_bf16 v[4:19], v[64:67], v[86:89], v[4:19]
	ds_read2_b64 v[86:89], v93 offset0:44 offset1:46
	s_waitcnt lgkmcnt(0)
	v_mfma_f32_32x32x16_bf16 v[4:19], v[60:63], v[86:89], v[4:19]
	ds_read2_b64 v[86:89], v93 offset0:48 offset1:50
	s_waitcnt lgkmcnt(0)
	v_mfma_f32_32x32x16_bf16 v[4:19], v[68:71], v[86:89], v[4:19]
	ds_read2_b64 v[86:89], v93 offset0:52 offset1:54
	s_waitcnt lgkmcnt(0)
	v_mfma_f32_32x32x16_bf16 v[4:19], v[72:75], v[86:89], v[4:19]
	ds_read2_b64 v[86:89], v93 offset0:56 offset1:58
	s_waitcnt lgkmcnt(0)
	v_mfma_f32_32x32x16_bf16 v[4:19], v[76:79], v[86:89], v[4:19]
	ds_read2_b64 v[86:89], v93 offset0:60 offset1:62
	s_waitcnt lgkmcnt(0)
	v_mfma_f32_32x32x16_bf16 v[4:19], v[80:83], v[86:89], v[4:19]
	s_nop 11
	v_cvt_pk_bf16_f32 v4, v4, v5
	ds_write_b16 v84, v4
	ds_write_b16_d16_hi v84, v4 offset:272
	v_cvt_pk_bf16_f32 v4, v6, v7
	ds_write_b16 v84, v4 offset:544
	ds_write_b16_d16_hi v84, v4 offset:816
	v_cvt_pk_bf16_f32 v4, v8, v9
	ds_write_b16 v84, v4 offset:2176
	ds_write_b16_d16_hi v84, v4 offset:2448
	v_cvt_pk_bf16_f32 v4, v10, v11
	ds_write_b16 v84, v4 offset:2720
	ds_write_b16_d16_hi v84, v4 offset:2992
	v_cvt_pk_bf16_f32 v4, v12, v13
	ds_write_b16 v84, v4 offset:4352
	ds_write_b16_d16_hi v84, v4 offset:4624
	v_cvt_pk_bf16_f32 v4, v14, v15
	ds_write_b16 v84, v4 offset:4896
	ds_write_b16_d16_hi v84, v4 offset:5168
	v_cvt_pk_bf16_f32 v4, v16, v17
	ds_write_b16 v84, v4 offset:6528
	ds_write_b16_d16_hi v84, v4 offset:6800
	v_cvt_pk_bf16_f32 v4, v18, v19
	ds_write_b16 v84, v4 offset:7072
	ds_write_b16_d16_hi v84, v4 offset:7344
	v_add_u32_e32 v85, 0x4000, v93
	ds_read2_b64 v[4:7], v85 offset0:32 offset1:34
	ds_read2_b64 v[86:89], v85 offset0:36 offset1:38
	ds_read2_b64 v[94:97], v85 offset0:40 offset1:42
	ds_read2_b64 v[98:101], v85 offset0:44 offset1:46
	ds_read2_b64 v[102:105], v85 offset0:48 offset1:50
	s_waitcnt lgkmcnt(4)
	v_mfma_f32_32x32x16_bf16 v[4:19], v[20:23], v[4:7], 0
	s_waitcnt lgkmcnt(3)
	v_mfma_f32_32x32x16_bf16 v[4:19], v[24:27], v[86:89], v[4:19]
	ds_read2_b64 v[86:89], v85 offset0:52 offset1:54
	s_waitcnt lgkmcnt(3)
	v_mfma_f32_32x32x16_bf16 v[4:19], v[32:35], v[94:97], v[4:19]
	ds_read2_b64 v[94:97], v85 offset0:56 offset1:58
	s_waitcnt lgkmcnt(3)
	v_mfma_f32_32x32x16_bf16 v[4:19], v[28:31], v[98:101], v[4:19]
	ds_read2_b64 v[98:101], v85 offset0:60 offset1:62
	s_waitcnt lgkmcnt(3)
	v_mfma_f32_32x32x16_bf16 v[4:19], v[36:39], v[102:105], v[4:19]
	ds_read2_b64 v[102:105], v85 offset0:64 offset1:66
	s_waitcnt lgkmcnt(3)
	v_mfma_f32_32x32x16_bf16 v[4:19], v[40:43], v[86:89], v[4:19]
	ds_read2_b64 v[86:89], v85 offset0:68 offset1:70
	s_waitcnt lgkmcnt(3)
	v_mfma_f32_32x32x16_bf16 v[4:19], v[48:51], v[94:97], v[4:19]
	ds_read2_b64 v[94:97], v85 offset0:72 offset1:74
	s_waitcnt lgkmcnt(3)
	v_mfma_f32_32x32x16_bf16 v[4:19], v[44:47], v[98:101], v[4:19]
	ds_read2_b64 v[98:101], v85 offset0:76 offset1:78
	s_waitcnt lgkmcnt(3)
	v_mfma_f32_32x32x16_bf16 v[4:19], v[52:55], v[102:105], v[4:19]
	ds_read2_b64 v[102:105], v85 offset0:80 offset1:82
	s_waitcnt lgkmcnt(3)
	v_mfma_f32_32x32x16_bf16 v[4:19], v[56:59], v[86:89], v[4:19]
	ds_read2_b64 v[86:89], v85 offset0:84 offset1:86
	s_waitcnt lgkmcnt(3)
	v_mfma_f32_32x32x16_bf16 v[4:19], v[64:67], v[94:97], v[4:19]
	ds_read2_b64 v[94:97], v85 offset0:88 offset1:90
	s_waitcnt lgkmcnt(3)
	v_mfma_f32_32x32x16_bf16 v[4:19], v[60:63], v[98:101], v[4:19]
	ds_read2_b64 v[98:101], v85 offset0:92 offset1:94
	s_waitcnt lgkmcnt(3)
	v_mfma_f32_32x32x16_bf16 v[4:19], v[68:71], v[102:105], v[4:19]
	s_waitcnt lgkmcnt(2)
	v_mfma_f32_32x32x16_bf16 v[4:19], v[72:75], v[86:89], v[4:19]
	s_waitcnt lgkmcnt(1)
	v_mfma_f32_32x32x16_bf16 v[4:19], v[76:79], v[94:97], v[4:19]
	s_waitcnt lgkmcnt(0)
	v_mfma_f32_32x32x16_bf16 v[4:19], v[80:83], v[98:101], v[4:19]
	s_nop 11
	v_cvt_pk_bf16_f32 v4, v4, v5
	ds_write_b16 v84, v4 offset:64
	ds_write_b16_d16_hi v84, v4 offset:336
	v_cvt_pk_bf16_f32 v4, v6, v7
	ds_write_b16 v84, v4 offset:608
	ds_write_b16_d16_hi v84, v4 offset:880
	v_cvt_pk_bf16_f32 v4, v8, v9
	ds_write_b16 v84, v4 offset:2240
	ds_write_b16_d16_hi v84, v4 offset:2512
	v_cvt_pk_bf16_f32 v4, v10, v11
	ds_write_b16 v84, v4 offset:2784
	ds_write_b16_d16_hi v84, v4 offset:3056
	v_cvt_pk_bf16_f32 v4, v12, v13
	ds_write_b16 v84, v4 offset:4416
	ds_write_b16_d16_hi v84, v4 offset:4688
	v_cvt_pk_bf16_f32 v4, v14, v15
	ds_write_b16 v84, v4 offset:4960
	ds_write_b16_d16_hi v84, v4 offset:5232
	v_cvt_pk_bf16_f32 v4, v16, v17
	ds_write_b16 v84, v4 offset:6592
	ds_write_b16_d16_hi v84, v4 offset:6864
	v_cvt_pk_bf16_f32 v4, v18, v19
	ds_write_b16 v84, v4 offset:7136
	ds_write_b16_d16_hi v84, v4 offset:7408
	v_mad_u32_u24 v85, v214, s8, v92
	ds_read2_b64 v[4:7], v85 offset1:2
	ds_read2_b64 v[86:89], v85 offset0:4 offset1:6
	ds_read2_b64 v[94:97], v85 offset0:8 offset1:10
	ds_read2_b64 v[98:101], v85 offset0:12 offset1:14
	ds_read2_b64 v[102:105], v85 offset0:16 offset1:18
	s_waitcnt lgkmcnt(4)
	v_mfma_f32_32x32x16_bf16 v[4:19], v[20:23], v[4:7], 0
	s_waitcnt lgkmcnt(3)
	v_mfma_f32_32x32x16_bf16 v[4:19], v[24:27], v[86:89], v[4:19]
	ds_read2_b64 v[86:89], v85 offset0:20 offset1:22
	s_waitcnt lgkmcnt(3)
	v_mfma_f32_32x32x16_bf16 v[4:19], v[32:35], v[94:97], v[4:19]
	ds_read2_b64 v[94:97], v85 offset0:24 offset1:26
	s_waitcnt lgkmcnt(3)
	v_mfma_f32_32x32x16_bf16 v[4:19], v[28:31], v[98:101], v[4:19]
	ds_read2_b64 v[98:101], v85 offset0:28 offset1:30
	s_waitcnt lgkmcnt(3)
	v_mfma_f32_32x32x16_bf16 v[4:19], v[36:39], v[102:105], v[4:19]
	ds_read2_b64 v[102:105], v85 offset0:32 offset1:34
	s_waitcnt lgkmcnt(3)
	v_mfma_f32_32x32x16_bf16 v[4:19], v[40:43], v[86:89], v[4:19]
	ds_read2_b64 v[86:89], v85 offset0:36 offset1:38
	s_waitcnt lgkmcnt(3)
	v_mfma_f32_32x32x16_bf16 v[4:19], v[48:51], v[94:97], v[4:19]
	ds_read2_b64 v[94:97], v85 offset0:40 offset1:42
	s_waitcnt lgkmcnt(3)
	v_mfma_f32_32x32x16_bf16 v[4:19], v[44:47], v[98:101], v[4:19]
	ds_read2_b64 v[98:101], v85 offset0:44 offset1:46
	s_waitcnt lgkmcnt(3)
	v_mfma_f32_32x32x16_bf16 v[4:19], v[52:55], v[102:105], v[4:19]
	ds_read2_b64 v[102:105], v85 offset0:48 offset1:50
	s_waitcnt lgkmcnt(3)
	v_mfma_f32_32x32x16_bf16 v[4:19], v[56:59], v[86:89], v[4:19]
	ds_read2_b64 v[86:89], v85 offset0:52 offset1:54
	s_waitcnt lgkmcnt(3)
	v_mfma_f32_32x32x16_bf16 v[4:19], v[64:67], v[94:97], v[4:19]
	ds_read2_b64 v[94:97], v85 offset0:56 offset1:58
	s_waitcnt lgkmcnt(3)
	v_mfma_f32_32x32x16_bf16 v[4:19], v[60:63], v[98:101], v[4:19]
	ds_read2_b64 v[98:101], v85 offset0:60 offset1:62
	s_waitcnt lgkmcnt(3)
	v_mfma_f32_32x32x16_bf16 v[4:19], v[68:71], v[102:105], v[4:19]
	s_waitcnt lgkmcnt(2)
	v_mfma_f32_32x32x16_bf16 v[4:19], v[72:75], v[86:89], v[4:19]
	s_waitcnt lgkmcnt(1)
	v_mfma_f32_32x32x16_bf16 v[4:19], v[76:79], v[94:97], v[4:19]
	s_waitcnt lgkmcnt(0)
	v_mfma_f32_32x32x16_bf16 v[4:19], v[80:83], v[98:101], v[4:19]
	s_nop 11
	v_cvt_pk_bf16_f32 v4, v4, v5
	ds_write_b16 v84, v4 offset:128
	ds_write_b16_d16_hi v84, v4 offset:400
	v_cvt_pk_bf16_f32 v4, v6, v7
	ds_write_b16 v84, v4 offset:672
	ds_write_b16_d16_hi v84, v4 offset:944
	v_cvt_pk_bf16_f32 v4, v8, v9
	ds_write_b16 v84, v4 offset:2304
	ds_write_b16_d16_hi v84, v4 offset:2576
	v_cvt_pk_bf16_f32 v4, v10, v11
	ds_write_b16 v84, v4 offset:2848
	ds_write_b16_d16_hi v84, v4 offset:3120
	v_cvt_pk_bf16_f32 v4, v12, v13
	ds_write_b16 v84, v4 offset:4480
	ds_write_b16_d16_hi v84, v4 offset:4752
	v_cvt_pk_bf16_f32 v4, v14, v15
	ds_write_b16 v84, v4 offset:5024
	ds_write_b16_d16_hi v84, v4 offset:5296
	v_cvt_pk_bf16_f32 v4, v16, v17
	ds_write_b16 v84, v4 offset:6656
	ds_write_b16_d16_hi v84, v4 offset:6928
	v_cvt_pk_bf16_f32 v4, v18, v19
	ds_write_b16 v84, v4 offset:7200
	ds_write_b16_d16_hi v84, v4 offset:7472
	v_mad_u32_u24 v85, v212, s8, v92
	ds_read2_b64 v[4:7], v85 offset1:2
	ds_read2_b64 v[86:89], v85 offset0:4 offset1:6
	ds_read2_b64 v[94:97], v85 offset0:8 offset1:10
	ds_read2_b64 v[98:101], v85 offset0:12 offset1:14
	ds_read2_b64 v[102:105], v85 offset0:16 offset1:18
	s_waitcnt lgkmcnt(4)
	v_mfma_f32_32x32x16_bf16 v[4:19], v[20:23], v[4:7], 0
	s_waitcnt lgkmcnt(3)
	v_mfma_f32_32x32x16_bf16 v[4:19], v[24:27], v[86:89], v[4:19]
	ds_read2_b64 v[86:89], v85 offset0:20 offset1:22
	s_waitcnt lgkmcnt(3)
	v_mfma_f32_32x32x16_bf16 v[4:19], v[32:35], v[94:97], v[4:19]
	ds_read2_b64 v[94:97], v85 offset0:24 offset1:26
	s_waitcnt lgkmcnt(3)
	v_mfma_f32_32x32x16_bf16 v[4:19], v[28:31], v[98:101], v[4:19]
	ds_read2_b64 v[98:101], v85 offset0:28 offset1:30
	s_waitcnt lgkmcnt(3)
	v_mfma_f32_32x32x16_bf16 v[4:19], v[36:39], v[102:105], v[4:19]
	ds_read2_b64 v[102:105], v85 offset0:32 offset1:34
	s_waitcnt lgkmcnt(3)
	v_mfma_f32_32x32x16_bf16 v[4:19], v[40:43], v[86:89], v[4:19]
	ds_read2_b64 v[86:89], v85 offset0:36 offset1:38
	s_waitcnt lgkmcnt(3)
	v_mfma_f32_32x32x16_bf16 v[4:19], v[48:51], v[94:97], v[4:19]
	ds_read2_b64 v[94:97], v85 offset0:40 offset1:42
	s_waitcnt lgkmcnt(3)
	v_mfma_f32_32x32x16_bf16 v[4:19], v[44:47], v[98:101], v[4:19]
	ds_read2_b64 v[98:101], v85 offset0:44 offset1:46
	s_waitcnt lgkmcnt(3)
	v_mfma_f32_32x32x16_bf16 v[4:19], v[52:55], v[102:105], v[4:19]
	ds_read2_b64 v[102:105], v85 offset0:48 offset1:50
	s_waitcnt lgkmcnt(3)
	v_mfma_f32_32x32x16_bf16 v[4:19], v[56:59], v[86:89], v[4:19]
	ds_read2_b64 v[86:89], v85 offset0:52 offset1:54
	s_waitcnt lgkmcnt(3)
	v_mfma_f32_32x32x16_bf16 v[4:19], v[64:67], v[94:97], v[4:19]
	ds_read2_b64 v[94:97], v85 offset0:56 offset1:58
	s_waitcnt lgkmcnt(3)
	v_mfma_f32_32x32x16_bf16 v[4:19], v[60:63], v[98:101], v[4:19]
	ds_read2_b64 v[98:101], v85 offset0:60 offset1:62
	s_waitcnt lgkmcnt(3)
	v_mfma_f32_32x32x16_bf16 v[4:19], v[68:71], v[102:105], v[4:19]
	s_waitcnt lgkmcnt(2)
	v_mfma_f32_32x32x16_bf16 v[4:19], v[72:75], v[86:89], v[4:19]
	s_waitcnt lgkmcnt(1)
	v_mfma_f32_32x32x16_bf16 v[4:19], v[76:79], v[94:97], v[4:19]
	s_waitcnt lgkmcnt(0)
	v_mfma_f32_32x32x16_bf16 v[4:19], v[80:83], v[98:101], v[4:19]
	s_nop 11
	v_cvt_pk_bf16_f32 v4, v4, v5
	ds_write_b16 v84, v4 offset:192
	ds_write_b16_d16_hi v84, v4 offset:464
	v_cvt_pk_bf16_f32 v4, v6, v7
	ds_write_b16 v84, v4 offset:736
	ds_write_b16_d16_hi v84, v4 offset:1008
	v_cvt_pk_bf16_f32 v4, v8, v9
	ds_write_b16 v84, v4 offset:2368
	ds_write_b16_d16_hi v84, v4 offset:2640
	v_cvt_pk_bf16_f32 v4, v10, v11
	ds_write_b16 v84, v4 offset:2912
	ds_write_b16_d16_hi v84, v4 offset:3184
	v_cvt_pk_bf16_f32 v4, v12, v13
	ds_write_b16 v84, v4 offset:4544
	ds_write_b16_d16_hi v84, v4 offset:4816
	v_cvt_pk_bf16_f32 v4, v14, v15
	ds_write_b16 v84, v4 offset:5088
	ds_write_b16_d16_hi v84, v4 offset:5360
	v_cvt_pk_bf16_f32 v4, v16, v17
	ds_write_b16 v84, v4 offset:6720
	ds_write_b16_d16_hi v84, v4 offset:6992
	v_cvt_pk_bf16_f32 v4, v18, v19
	ds_write_b16 v84, v4 offset:7264
	ds_write_b16_d16_hi v84, v4 offset:7536
	v_mul_u32_u24_e32 v4, 0x110, v201
	v_add3_u32 v6, s4, v4, v2
	ds_read_b128 v[8:11], v6
	s_mulk_i32 s39, 0xc00
	s_mul_hi_u32 s41, s38, 0xc00
	s_waitcnt vmcnt(7)
	v_lshlrev_b32_e32 v14, 16, v160
	v_and_b32_e32 v15, 0xffff0000, v160
	s_waitcnt lgkmcnt(0)
	v_lshlrev_b32_e32 v12, 16, v8
	v_and_b32_e32 v13, 0xffff0000, v8
	s_add_i32 s41, s41, s39
	s_mulk_i32 s38, 0xc00
	v_pk_mul_f32 v[12:13], v[14:15], v[12:13]
	s_add_u32 s38, s36, s38
	v_cvt_pk_bf16_f32 v8, v12, v13
	v_lshlrev_b32_e32 v12, 16, v9
	v_and_b32_e32 v13, 0xffff0000, v9
	v_lshlrev_b32_e32 v14, 16, v161
	v_and_b32_e32 v15, 0xffff0000, v161
	s_addc_u32 s39, s37, s41
	v_pk_mul_f32 v[12:13], v[14:15], v[12:13]
	s_add_u32 s38, s38, s24
	v_mul_u32_u24_e32 v4, 0x600, v201
	v_cvt_pk_bf16_f32 v9, v12, v13
	v_lshlrev_b32_e32 v12, 16, v10
	v_and_b32_e32 v13, 0xffff0000, v10
	v_lshlrev_b32_e32 v14, 16, v162
	v_and_b32_e32 v15, 0xffff0000, v162
	s_addc_u32 s39, s39, 0
	v_lshlrev_b32_e32 v4, 1, v4
	v_mov_b32_e32 v5, v3
	v_pk_mul_f32 v[12:13], v[14:15], v[12:13]
	v_lshl_add_u64 v[4:5], s[38:39], 0, v[4:5]
	v_cvt_pk_bf16_f32 v10, v12, v13
	v_lshlrev_b32_e32 v12, 16, v11
	v_and_b32_e32 v13, 0xffff0000, v11
	v_lshlrev_b32_e32 v14, 16, v163
	v_and_b32_e32 v15, 0xffff0000, v163
	v_lshl_add_u64 v[4:5], v[4:5], 0, v[2:3]
	v_pk_mul_f32 v[12:13], v[14:15], v[12:13]
	s_waitcnt vmcnt(6)
	v_lshlrev_b32_e32 v14, 16, v156
	v_cvt_pk_bf16_f32 v11, v12, v13
	v_add_co_u32_e32 v12, vcc, s47, v4
	v_and_b32_e32 v15, 0xffff0000, v156
	s_nop 0
	v_addc_co_u32_e32 v13, vcc, 0, v5, vcc
	global_store_dwordx4 v[12:13], v[8:11], off offset:2048 sc1
	ds_read_b128 v[8:11], v6 offset:1088
	s_add_i32 s40, s40, s10
	s_add_i32 s14, s14, s28
	s_add_i32 s1, s1, s29
	s_cmpk_gt_i32 s40, 0xff
	s_waitcnt lgkmcnt(0)
	v_lshlrev_b32_e32 v12, 16, v8
	v_and_b32_e32 v13, 0xffff0000, v8
	v_pk_mul_f32 v[12:13], v[14:15], v[12:13]
	v_lshlrev_b32_e32 v14, 16, v157
	v_cvt_pk_bf16_f32 v8, v12, v13
	v_lshlrev_b32_e32 v12, 16, v9
	v_and_b32_e32 v13, 0xffff0000, v9
	v_and_b32_e32 v15, 0xffff0000, v157
	v_pk_mul_f32 v[12:13], v[14:15], v[12:13]
	v_lshlrev_b32_e32 v14, 16, v158
	v_cvt_pk_bf16_f32 v9, v12, v13
	v_lshlrev_b32_e32 v12, 16, v10
	v_and_b32_e32 v13, 0xffff0000, v10
	v_and_b32_e32 v15, 0xffff0000, v158
	v_pk_mul_f32 v[12:13], v[14:15], v[12:13]
	v_lshlrev_b32_e32 v14, 16, v159
	v_cvt_pk_bf16_f32 v10, v12, v13
	v_lshlrev_b32_e32 v12, 16, v11
	v_and_b32_e32 v13, 0xffff0000, v11
	v_and_b32_e32 v15, 0xffff0000, v159
	v_pk_mul_f32 v[12:13], v[14:15], v[12:13]
	s_waitcnt vmcnt(6)
	v_lshlrev_b32_e32 v14, 16, v152
	v_cvt_pk_bf16_f32 v11, v12, v13
	v_add_co_u32_e32 v12, vcc, s48, v4
	v_and_b32_e32 v15, 0xffff0000, v152
	s_nop 0
	v_addc_co_u32_e32 v13, vcc, 0, v5, vcc
	global_store_dwordx4 v[12:13], v[8:11], off offset:2048 sc1
	ds_read_b128 v[8:11], v6 offset:2176
	s_waitcnt lgkmcnt(0)
	v_lshlrev_b32_e32 v12, 16, v8
	v_and_b32_e32 v13, 0xffff0000, v8
	v_pk_mul_f32 v[12:13], v[14:15], v[12:13]
	v_lshlrev_b32_e32 v14, 16, v153
	v_cvt_pk_bf16_f32 v8, v12, v13
	v_lshlrev_b32_e32 v12, 16, v9
	v_and_b32_e32 v13, 0xffff0000, v9
	v_and_b32_e32 v15, 0xffff0000, v153
	v_pk_mul_f32 v[12:13], v[14:15], v[12:13]
	v_lshlrev_b32_e32 v14, 16, v154
	v_cvt_pk_bf16_f32 v9, v12, v13
	v_lshlrev_b32_e32 v12, 16, v10
	v_and_b32_e32 v13, 0xffff0000, v10
	v_and_b32_e32 v15, 0xffff0000, v154
	v_pk_mul_f32 v[12:13], v[14:15], v[12:13]
	v_lshlrev_b32_e32 v14, 16, v155
	v_cvt_pk_bf16_f32 v10, v12, v13
	v_lshlrev_b32_e32 v12, 16, v11
	v_and_b32_e32 v13, 0xffff0000, v11
	v_and_b32_e32 v15, 0xffff0000, v155
	v_pk_mul_f32 v[12:13], v[14:15], v[12:13]
	s_waitcnt vmcnt(6)
	v_lshlrev_b32_e32 v14, 16, v148
	v_cvt_pk_bf16_f32 v11, v12, v13
	v_add_co_u32_e32 v12, vcc, s49, v4
	v_and_b32_e32 v15, 0xffff0000, v148
	s_nop 0
	v_addc_co_u32_e32 v13, vcc, 0, v5, vcc
	global_store_dwordx4 v[12:13], v[8:11], off offset:2048 sc1
	ds_read_b128 v[8:11], v6 offset:3264
	s_waitcnt lgkmcnt(0)
	v_lshlrev_b32_e32 v12, 16, v8
	v_and_b32_e32 v13, 0xffff0000, v8
	v_pk_mul_f32 v[12:13], v[14:15], v[12:13]
	v_lshlrev_b32_e32 v14, 16, v149
	v_cvt_pk_bf16_f32 v8, v12, v13
	v_lshlrev_b32_e32 v12, 16, v9
	v_and_b32_e32 v13, 0xffff0000, v9
	v_and_b32_e32 v15, 0xffff0000, v149
	v_pk_mul_f32 v[12:13], v[14:15], v[12:13]
	v_lshlrev_b32_e32 v14, 16, v150
	v_cvt_pk_bf16_f32 v9, v12, v13
	v_lshlrev_b32_e32 v12, 16, v10
	v_and_b32_e32 v13, 0xffff0000, v10
	v_and_b32_e32 v15, 0xffff0000, v150
	v_pk_mul_f32 v[12:13], v[14:15], v[12:13]
	v_lshlrev_b32_e32 v14, 16, v151
	v_cvt_pk_bf16_f32 v10, v12, v13
	v_lshlrev_b32_e32 v12, 16, v11
	v_and_b32_e32 v13, 0xffff0000, v11
	v_and_b32_e32 v15, 0xffff0000, v151
	v_pk_mul_f32 v[12:13], v[14:15], v[12:13]
	s_waitcnt vmcnt(6)
	v_lshlrev_b32_e32 v14, 16, v144
	v_cvt_pk_bf16_f32 v11, v12, v13
	v_add_co_u32_e32 v12, vcc, s54, v4
	v_and_b32_e32 v15, 0xffff0000, v144
	s_nop 0
	v_addc_co_u32_e32 v13, vcc, 0, v5, vcc
	global_store_dwordx4 v[12:13], v[8:11], off offset:2048 sc1
	ds_read_b128 v[8:11], v6 offset:4352
	s_waitcnt lgkmcnt(0)
	v_lshlrev_b32_e32 v12, 16, v8
	v_and_b32_e32 v13, 0xffff0000, v8
	v_pk_mul_f32 v[12:13], v[14:15], v[12:13]
	v_lshlrev_b32_e32 v14, 16, v145
	v_cvt_pk_bf16_f32 v8, v12, v13
	v_lshlrev_b32_e32 v12, 16, v9
	v_and_b32_e32 v13, 0xffff0000, v9
	v_and_b32_e32 v15, 0xffff0000, v145
	v_pk_mul_f32 v[12:13], v[14:15], v[12:13]
	v_lshlrev_b32_e32 v14, 16, v146
	v_cvt_pk_bf16_f32 v9, v12, v13
	v_lshlrev_b32_e32 v12, 16, v10
	v_and_b32_e32 v13, 0xffff0000, v10
	v_and_b32_e32 v15, 0xffff0000, v146
	v_pk_mul_f32 v[12:13], v[14:15], v[12:13]
	v_lshlrev_b32_e32 v14, 16, v147
	v_cvt_pk_bf16_f32 v10, v12, v13
	v_lshlrev_b32_e32 v12, 16, v11
	v_and_b32_e32 v13, 0xffff0000, v11
	v_and_b32_e32 v15, 0xffff0000, v147
	v_pk_mul_f32 v[12:13], v[14:15], v[12:13]
	s_waitcnt vmcnt(6)
	v_lshlrev_b32_e32 v14, 16, v140
	v_cvt_pk_bf16_f32 v11, v12, v13
	v_add_co_u32_e32 v12, vcc, s94, v4
	v_and_b32_e32 v15, 0xffff0000, v140
	s_nop 0
	v_addc_co_u32_e32 v13, vcc, 0, v5, vcc
	global_store_dwordx4 v[12:13], v[8:11], off offset:2048 sc1
	ds_read_b128 v[8:11], v6 offset:5440
	s_waitcnt lgkmcnt(0)
	v_lshlrev_b32_e32 v12, 16, v8
	v_and_b32_e32 v13, 0xffff0000, v8
	v_pk_mul_f32 v[12:13], v[14:15], v[12:13]
	v_lshlrev_b32_e32 v14, 16, v141
	v_cvt_pk_bf16_f32 v8, v12, v13
	v_lshlrev_b32_e32 v12, 16, v9
	v_and_b32_e32 v13, 0xffff0000, v9
	v_and_b32_e32 v15, 0xffff0000, v141
	v_pk_mul_f32 v[12:13], v[14:15], v[12:13]
	v_lshlrev_b32_e32 v14, 16, v142
	v_cvt_pk_bf16_f32 v9, v12, v13
	v_lshlrev_b32_e32 v12, 16, v10
	v_and_b32_e32 v13, 0xffff0000, v10
	v_and_b32_e32 v15, 0xffff0000, v142
	v_pk_mul_f32 v[12:13], v[14:15], v[12:13]
	v_lshlrev_b32_e32 v14, 16, v143
	v_cvt_pk_bf16_f32 v10, v12, v13
	v_lshlrev_b32_e32 v12, 16, v11
	v_and_b32_e32 v13, 0xffff0000, v11
	v_and_b32_e32 v15, 0xffff0000, v143
	v_pk_mul_f32 v[12:13], v[14:15], v[12:13]
	s_waitcnt vmcnt(6)
	v_lshlrev_b32_e32 v14, 16, v136
	v_cvt_pk_bf16_f32 v11, v12, v13
	v_add_co_u32_e32 v12, vcc, s97, v4
	v_and_b32_e32 v15, 0xffff0000, v136
	s_nop 0
	v_addc_co_u32_e32 v13, vcc, 0, v5, vcc
	global_store_dwordx4 v[12:13], v[8:11], off offset:2048 sc1
	ds_read_b128 v[8:11], v6 offset:6528
	s_waitcnt lgkmcnt(0)
	v_lshlrev_b32_e32 v12, 16, v8
	v_and_b32_e32 v13, 0xffff0000, v8
	v_pk_mul_f32 v[12:13], v[14:15], v[12:13]
	v_lshlrev_b32_e32 v14, 16, v137
	v_cvt_pk_bf16_f32 v8, v12, v13
	v_lshlrev_b32_e32 v12, 16, v9
	v_and_b32_e32 v13, 0xffff0000, v9
	v_and_b32_e32 v15, 0xffff0000, v137
	v_pk_mul_f32 v[12:13], v[14:15], v[12:13]
	v_lshlrev_b32_e32 v14, 16, v138
	v_cvt_pk_bf16_f32 v9, v12, v13
	v_lshlrev_b32_e32 v12, 16, v10
	v_and_b32_e32 v13, 0xffff0000, v10
	v_and_b32_e32 v15, 0xffff0000, v138
	v_pk_mul_f32 v[12:13], v[14:15], v[12:13]
	v_lshlrev_b32_e32 v14, 16, v139
	v_cvt_pk_bf16_f32 v10, v12, v13
	v_lshlrev_b32_e32 v12, 16, v11
	v_and_b32_e32 v13, 0xffff0000, v11
	v_and_b32_e32 v15, 0xffff0000, v139
	v_pk_mul_f32 v[12:13], v[14:15], v[12:13]
	s_nop 0
	v_cvt_pk_bf16_f32 v11, v12, v13
	v_add_co_u32_e32 v12, vcc, s55, v4
	s_nop 1
	v_addc_co_u32_e32 v13, vcc, 0, v5, vcc
	global_store_dwordx4 v[12:13], v[8:11], off offset:2048 sc1
	ds_read_b128 v[6:9], v6 offset:7616
	s_waitcnt vmcnt(7)
	v_lshlrev_b32_e32 v12, 16, v132
	v_and_b32_e32 v13, 0xffff0000, v132
	v_add_co_u32_e32 v4, vcc, 0xc615000, v4
	s_waitcnt lgkmcnt(0)
	v_lshlrev_b32_e32 v10, 16, v6
	v_and_b32_e32 v11, 0xffff0000, v6
	v_pk_mul_f32 v[10:11], v[12:13], v[10:11]
	v_lshlrev_b32_e32 v12, 16, v133
	v_cvt_pk_bf16_f32 v6, v10, v11
	v_lshlrev_b32_e32 v10, 16, v7
	v_and_b32_e32 v11, 0xffff0000, v7
	v_and_b32_e32 v13, 0xffff0000, v133
	v_pk_mul_f32 v[10:11], v[12:13], v[10:11]
	v_lshlrev_b32_e32 v12, 16, v134
	v_cvt_pk_bf16_f32 v7, v10, v11
	v_lshlrev_b32_e32 v10, 16, v8
	v_and_b32_e32 v11, 0xffff0000, v8
	v_and_b32_e32 v13, 0xffff0000, v134
	v_pk_mul_f32 v[10:11], v[12:13], v[10:11]
	v_lshlrev_b32_e32 v12, 16, v135
	v_cvt_pk_bf16_f32 v8, v10, v11
	v_lshlrev_b32_e32 v10, 16, v9
	v_and_b32_e32 v11, 0xffff0000, v9
	v_and_b32_e32 v13, 0xffff0000, v135
	v_pk_mul_f32 v[10:11], v[12:13], v[10:11]
	v_addc_co_u32_e32 v5, vcc, 0, v5, vcc
	v_cvt_pk_bf16_f32 v9, v10, v11
	global_store_dwordx4 v[4:5], v[6:9], off offset:2048 sc1
	s_barrier
	s_cbranch_scc0 .LBB0_547

.LBB0_758:
	s_ashr_i32 s40, s43, 7
	s_lshl_b32 s24, s40, 8
	s_add_i32 s44, s24, s95
	s_ashr_i32 s45, s44, 31
	s_lshl_b64 s[44:45], s[44:45], 10
	s_add_u32 s41, s92, s44
	s_addc_u32 s47, s9, s45
	s_and_b32 s24, s42, 0x180
	s_lshl_b32 s24, s24, 1
	s_add_u32 s46, s41, s24
	s_addc_u32 s47, s47, 0
	v_mov_b32_e32 v211, v204
	s_add_u32 s41, s56, s44
	s_addc_u32 s45, s57, s45
	v_ashrrev_i32_e32 v62, 5, v211
	v_and_b32_e32 v69, -8, v62
	s_add_u32 s44, s41, s24
	v_and_b32_e32 v68, 0xff, v211
	v_lshlrev_b32_e32 v4, 3, v69
	s_addc_u32 s45, s45, 0
	v_lshlrev_b32_e32 v2, 10, v68
	v_ashrrev_i32_e32 v5, 31, v4
	v_or_b32_e32 v70, 1, v69
	v_lshl_add_u64 v[60:61], s[46:47], 0, v[2:3]
	v_lshl_add_u64 v[64:65], s[44:45], 0, v[2:3]
	v_lshlrev_b64 v[8:9], 1, v[4:5]
	v_lshlrev_b32_e32 v16, 3, v70
	v_or_b32_e32 v71, 2, v69
	v_or_b32_e32 v73, 4, v69
	v_lshl_add_u64 v[28:29], v[60:61], 0, v[8:9]
	v_lshl_add_u64 v[8:9], v[64:65], 0, v[8:9]
	v_ashrrev_i32_e32 v17, 31, v16
	v_lshlrev_b32_e32 v24, 3, v71
	v_or_b32_e32 v72, 3, v69
	v_lshlrev_b32_e32 v36, 3, v73
	global_load_dwordx4 v[4:7], v[28:29], off
	s_nop 0
	global_load_dwordx4 v[8:11], v[8:9], off
	s_nop 0
	global_load_dwordx4 v[12:15], v[28:29], off offset:16
	v_lshl_add_u64 v[16:17], v[16:17], 1, v[64:65]
	v_ashrrev_i32_e32 v25, 31, v24
	v_lshlrev_b32_e32 v32, 3, v72
	v_ashrrev_i32_e32 v37, 31, v36
	global_load_dwordx4 v[16:19], v[16:17], off
	s_nop 0
	global_load_dwordx4 v[20:23], v[28:29], off offset:32
	v_lshl_add_u64 v[24:25], v[24:25], 1, v[64:65]
	v_ashrrev_i32_e32 v33, 31, v32
	v_lshlrev_b64 v[40:41], 1, v[36:37]
	v_or_b32_e32 v74, 5, v69
	v_or_b32_e32 v75, 6, v69
	v_or_b32_e32 v76, 7, v62
	global_load_dwordx4 v[24:27], v[24:25], off
	s_nop 0
	global_load_dwordx4 v[28:31], v[28:29], off offset:48
	v_lshl_add_u64 v[32:33], v[32:33], 1, v[64:65]
	v_lshl_add_u64 v[52:53], v[60:61], 0, v[40:41]
	v_lshlrev_b32_e32 v48, 3, v74
	v_lshlrev_b32_e32 v56, 3, v75
	v_lshlrev_b32_e32 v62, 3, v76
	global_load_dwordx4 v[32:35], v[32:33], off
	v_lshl_add_u64 v[40:41], v[64:65], 0, v[40:41]
	global_load_dwordx4 v[36:39], v[52:53], off
	v_ashrrev_i32_e32 v49, 31, v48
	v_ashrrev_i32_e32 v57, 31, v56
	v_ashrrev_i32_e32 v63, 31, v62
	global_load_dwordx4 v[40:43], v[40:41], off
	v_lshl_add_u64 v[48:49], v[48:49], 1, v[64:65]
	global_load_dwordx4 v[44:47], v[52:53], off offset:16
	v_lshl_add_u64 v[56:57], v[56:57], 1, v[64:65]
	v_lshlrev_b64 v[66:67], 1, v[62:63]
	global_load_dwordx4 v[48:51], v[48:49], off
	v_lshl_add_u64 v[60:61], v[60:61], 0, v[66:67]
	global_load_dwordx4 v[56:59], v[56:57], off
	v_lshl_add_u64 v[64:65], v[64:65], 0, v[66:67]
	global_load_dwordx4 v[52:55], v[52:53], off offset:32
	v_mad_u32_u24 v77, v68, s31, 0
	global_load_dwordx4 v[60:63], v[60:61], off
	v_lshl_add_u32 v2, v68, 1, s11
	global_load_dwordx4 v[64:67], v[64:65], off
	v_lshl_add_u32 v78, v69, 4, v77
	v_mad_u64_u32 v[68:69], s[44:45], v69, s77, v[2:3]
	v_lshl_add_u32 v69, v70, 4, v77
	s_ashr_i32 s41, s40, 31
	s_lshl_b64 s[40:41], s[40:41], 13
	v_and_b32_e32 v213, 31, v211
	v_bfe_u32 v210, v211, 4, 2
	v_mov_b32_e32 v81, 0
	s_and_b32 s44, s14, 0x1f00
	s_add_u32 s44, s44, s89
	s_addc_u32 s45, 0, s60
	s_add_u32 s40, s44, s40
	s_addc_u32 s41, s45, s41
	v_or_b32_e32 v80, s40, v213
	v_mov_b64_e32 v[82:83], s[54:55]
	v_mad_u64_u32 v[82:83], s[44:45], v80, s16, v[82:83]
	v_lshrrev_b32_e32 v80, 2, v211
	v_mad_i32_i24 v83, s41, v238, v83
	v_and_b32_e32 v215, 8, v80
	v_lshl_add_u64 v[82:83], v[82:83], 0, s[24:25]
	v_lshlrev_b32_e32 v84, 1, v215
	v_mov_b32_e32 v85, v3
	v_lshl_add_u64 v[82:83], v[82:83], 0, v[84:85]
	v_add_co_u32_e32 v84, vcc, s17, v82
	s_nop 0
	v_addc_co_u32_e32 v85, vcc, 0, v83, vcc
	global_load_dwordx4 v[116:119], v[84:85], off
	v_lshl_add_u64 v[86:87], v[82:83], 0, s[64:65]
	global_load_dwordx4 v[188:191], v[86:87], off offset:32
	global_load_dwordx4 v[184:187], v[86:87], off offset:64
	global_load_dwordx4 v[180:183], v[86:87], off offset:96
	global_load_dwordx4 v[176:179], v[86:87], off offset:128
	global_load_dwordx4 v[168:171], v[86:87], off offset:160
	global_load_dwordx4 v[164:167], v[86:87], off offset:192
	s_mul_i32 s44, s41, 0x1800
	s_mul_hi_u32 s45, s40, 0x1800
	s_add_i32 s45, s45, s44
	s_mul_i32 s44, s40, 0x1800
	v_lshrrev_b32_e32 v80, 1, v211
	s_add_u32 s44, s54, s44
	v_and_b32_e32 v80, 16, v80
	v_mul_u32_u24_e32 v82, 0x110, v213
	s_addc_u32 s45, s55, s45
	v_add3_u32 v198, 0, v80, v82
	s_add_u32 s44, s44, s24
	v_mul_u32_u24_e32 v80, 0xc00, v210
	s_addc_u32 s45, s45, 0
	v_lshlrev_b32_e32 v80, 1, v80
	global_load_dwordx4 v[172:175], v[86:87], off offset:224
	v_lshl_add_u64 v[86:87], s[44:45], 0, v[80:81]
	v_lshlrev_b32_e32 v80, 4, v211
	v_and_b32_e32 v80, 0xf0, v80
	v_lshl_add_u64 v[86:87], v[86:87], 0, v[80:81]
	v_add_co_u32_e32 v88, vcc, s17, v86
	s_nop 0
	v_addc_co_u32_e32 v89, vcc, 0, v87, vcc
	v_add_co_u32_e32 v90, vcc, s20, v86
	s_nop 1
	v_addc_co_u32_e32 v91, vcc, 0, v87, vcc
	global_load_dwordx4 v[160:163], v[88:89], off offset:1024
	global_load_dwordx4 v[156:159], v[90:91], off offset:1024
	v_add_co_u32_e32 v88, vcc, s30, v86
	s_nop 1
	v_addc_co_u32_e32 v89, vcc, 0, v87, vcc
	v_add_co_u32_e32 v90, vcc, s63, v86
	s_nop 1
	v_addc_co_u32_e32 v91, vcc, 0, v87, vcc
	global_load_dwordx4 v[152:155], v[88:89], off offset:1024
	global_load_dwordx4 v[148:151], v[90:91], off offset:1024
	v_add_co_u32_e32 v88, vcc, s34, v86
	s_nop 1
	v_addc_co_u32_e32 v89, vcc, 0, v87, vcc
	v_add_co_u32_e32 v90, vcc, s35, v86
	s_nop 1
	v_addc_co_u32_e32 v91, vcc, 0, v87, vcc
	global_load_dwordx4 v[144:147], v[88:89], off offset:1024
	global_load_dwordx4 v[140:143], v[90:91], off offset:1024
	v_add_co_u32_e32 v88, vcc, s96, v86
	s_nop 1
	v_addc_co_u32_e32 v89, vcc, 0, v87, vcc
	v_add_co_u32_e32 v86, vcc, s0, v86
	s_nop 1
	v_addc_co_u32_e32 v87, vcc, 0, v87, vcc
	global_load_dwordx4 v[136:139], v[88:89], off offset:1024
	global_load_dwordx4 v[132:135], v[86:87], off offset:1024
	s_waitcnt vmcnt(31)
	ds_write_b128 v78, v[4:7]
	s_waitcnt vmcnt(30)
	ds_write_b16 v68, v8
	ds_write_b16_d16_hi v68, v8 offset:520
	ds_write_b16 v68, v9 offset:1040
	ds_write_b16_d16_hi v68, v9 offset:1560
	ds_write_b16 v68, v10 offset:2080
	ds_write_b16_d16_hi v68, v10 offset:2600
	ds_write_b16 v68, v11 offset:3120
	ds_write_b16_d16_hi v68, v11 offset:3640
	s_waitcnt vmcnt(29)
	ds_write_b128 v69, v[12:15]
	s_waitcnt vmcnt(28)
	ds_write_b16 v68, v16 offset:4160
	ds_write_b16_d16_hi v68, v16 offset:4680
	ds_write_b16 v68, v17 offset:5200
	ds_write_b16_d16_hi v68, v17 offset:5720
	ds_write_b16 v68, v18 offset:6240
	ds_write_b16_d16_hi v68, v18 offset:6760
	ds_write_b16 v68, v19 offset:7280
	ds_write_b16_d16_hi v68, v19 offset:7800
	v_lshl_add_u32 v4, v71, 4, v77
	s_waitcnt vmcnt(27)
	ds_write_b128 v4, v[20:23]
	s_waitcnt vmcnt(26)
	ds_write_b16 v68, v24 offset:8320
	ds_write_b16_d16_hi v68, v24 offset:8840
	ds_write_b16 v68, v25 offset:9360
	ds_write_b16_d16_hi v68, v25 offset:9880
	ds_write_b16 v68, v26 offset:10400
	ds_write_b16_d16_hi v68, v26 offset:10920
	ds_write_b16 v68, v27 offset:11440
	ds_write_b16_d16_hi v68, v27 offset:11960
	v_lshl_add_u32 v4, v72, 4, v77
	s_waitcnt vmcnt(25)
	ds_write_b128 v4, v[28:31]
	s_waitcnt vmcnt(24)
	ds_write_b16 v68, v32 offset:12480
	ds_write_b16_d16_hi v68, v32 offset:13000
	ds_write_b16 v68, v33 offset:13520
	ds_write_b16_d16_hi v68, v33 offset:14040
	ds_write_b16 v68, v34 offset:14560
	ds_write_b16_d16_hi v68, v34 offset:15080
	ds_write_b16 v68, v35 offset:15600
	ds_write_b16_d16_hi v68, v35 offset:16120
	v_lshl_add_u32 v4, v73, 4, v77
	s_waitcnt vmcnt(23)
	ds_write_b128 v4, v[36:39]
	s_waitcnt vmcnt(22)
	ds_write_b16 v68, v40 offset:16640
	ds_write_b16_d16_hi v68, v40 offset:17160
	ds_write_b16 v68, v41 offset:17680
	ds_write_b16_d16_hi v68, v41 offset:18200
	ds_write_b16 v68, v42 offset:18720
	ds_write_b16_d16_hi v68, v42 offset:19240
	ds_write_b16 v68, v43 offset:19760
	ds_write_b16_d16_hi v68, v43 offset:20280
	v_lshl_add_u32 v4, v74, 4, v77
	s_waitcnt vmcnt(21)
	ds_write_b128 v4, v[44:47]
	s_waitcnt vmcnt(20)
	ds_write_b16 v68, v48 offset:20800
	ds_write_b16_d16_hi v68, v48 offset:21320
	ds_write_b16 v68, v49 offset:21840
	ds_write_b16_d16_hi v68, v49 offset:22360
	ds_write_b16 v68, v50 offset:22880
	ds_write_b16_d16_hi v68, v50 offset:23400
	ds_write_b16 v68, v51 offset:23920
	ds_write_b16_d16_hi v68, v51 offset:24440
	v_lshl_add_u32 v4, v75, 4, v77
	s_waitcnt vmcnt(18)
	ds_write_b128 v4, v[52:55]
	ds_write_b16 v68, v56 offset:24960
	ds_write_b16_d16_hi v68, v56 offset:25480
	ds_write_b16 v68, v57 offset:26000
	ds_write_b16_d16_hi v68, v57 offset:26520
	ds_write_b16 v68, v58 offset:27040
	ds_write_b16_d16_hi v68, v58 offset:27560
	ds_write_b16 v68, v59 offset:28080
	ds_write_b16_d16_hi v68, v59 offset:28600
	v_lshl_add_u32 v4, v76, 4, v77
	s_waitcnt vmcnt(17)
	ds_write_b128 v4, v[60:63]
	v_mad_u64_u32 v[4:5], s[44:45], v76, s77, v[2:3]
	s_waitcnt vmcnt(16)
	ds_write_b16 v4, v64
	ds_write_b16_d16_hi v4, v64 offset:520
	ds_write_b16 v4, v65 offset:1040
	ds_write_b16_d16_hi v4, v65 offset:1560
	ds_write_b16 v4, v66 offset:2080
	ds_write_b16_d16_hi v4, v66 offset:2600
	ds_write_b16 v4, v67 offset:3120
	ds_write_b16_d16_hi v4, v67 offset:3640
	s_waitcnt lgkmcnt(0)
	s_barrier
	v_lshlrev_b32_e32 v2, 4, v211
	v_and_b32_e32 v2, 0xf0, v2
	ds_read_b128 v[4:7], v198
	ds_read_b128 v[20:23], v198 offset:32
	s_waitcnt vmcnt(15) lgkmcnt(1)
	v_mfma_f32_32x32x16_bf16 v[4:19], v[4:7], v[116:119], 0
	s_waitcnt vmcnt(14) lgkmcnt(0)
	v_mfma_f32_32x32x16_bf16 v[4:19], v[20:23], v[188:191], v[4:19]
	ds_read_b128 v[20:23], v198 offset:64
	s_waitcnt vmcnt(13) lgkmcnt(0)
	v_mfma_f32_32x32x16_bf16 v[4:19], v[20:23], v[184:187], v[4:19]
	ds_read_b128 v[20:23], v198 offset:96
	s_waitcnt vmcnt(12) lgkmcnt(0)
	v_mfma_f32_32x32x16_bf16 v[4:19], v[20:23], v[180:183], v[4:19]
	ds_read_b128 v[20:23], v198 offset:128
	s_waitcnt vmcnt(11) lgkmcnt(0)
	v_mfma_f32_32x32x16_bf16 v[4:19], v[20:23], v[176:179], v[4:19]
	ds_read_b128 v[20:23], v198 offset:160
	s_waitcnt vmcnt(10) lgkmcnt(0)
	v_mfma_f32_32x32x16_bf16 v[4:19], v[20:23], v[168:171], v[4:19]
	ds_read_b128 v[20:23], v198 offset:192
	s_waitcnt vmcnt(9) lgkmcnt(0)
	v_mfma_f32_32x32x16_bf16 v[4:19], v[20:23], v[164:167], v[4:19]
	ds_read_b128 v[20:23], v198 offset:224
	s_waitcnt vmcnt(8) lgkmcnt(0)
	v_mfma_f32_32x32x16_bf16 v[4:19], v[20:23], v[172:175], v[4:19]
	ds_read_b128 v[20:23], v198 offset:8704
	ds_read_b128 v[36:39], v198 offset:8736
	ds_read_b128 v[40:43], v198 offset:8768
	ds_read_b128 v[44:47], v198 offset:8800
	ds_read_b128 v[48:51], v198 offset:8832
	s_waitcnt lgkmcnt(4)
	v_mfma_f32_32x32x16_bf16 v[20:35], v[20:23], v[116:119], 0
	s_waitcnt lgkmcnt(3)
	v_mfma_f32_32x32x16_bf16 v[20:35], v[36:39], v[188:191], v[20:35]
	ds_read_b128 v[36:39], v198 offset:8864
	s_waitcnt lgkmcnt(3)
	v_mfma_f32_32x32x16_bf16 v[20:35], v[40:43], v[184:187], v[20:35]
	ds_read_b128 v[40:43], v198 offset:8896
	s_waitcnt lgkmcnt(3)
	v_mfma_f32_32x32x16_bf16 v[20:35], v[44:47], v[180:183], v[20:35]
	ds_read_b128 v[44:47], v198 offset:8928
	s_waitcnt lgkmcnt(3)
	v_mfma_f32_32x32x16_bf16 v[20:35], v[48:51], v[176:179], v[20:35]
	s_waitcnt lgkmcnt(2)
	v_mfma_f32_32x32x16_bf16 v[20:35], v[36:39], v[168:171], v[20:35]
	s_waitcnt lgkmcnt(1)
	v_mfma_f32_32x32x16_bf16 v[20:35], v[40:43], v[164:167], v[20:35]
	s_waitcnt lgkmcnt(0)
	v_mfma_f32_32x32x16_bf16 v[20:35], v[44:47], v[172:175], v[20:35]
	ds_read_b128 v[36:39], v198 offset:17408
	ds_read_b128 v[52:55], v198 offset:17440
	ds_read_b128 v[56:59], v198 offset:17472
	ds_read_b128 v[60:63], v198 offset:17504
	ds_read_b128 v[64:67], v198 offset:17536
	v_or_b32_e32 v214, 64, v213
	s_waitcnt lgkmcnt(4)
	v_mfma_f32_32x32x16_bf16 v[36:51], v[36:39], v[116:119], 0
	s_waitcnt lgkmcnt(3)
	v_mfma_f32_32x32x16_bf16 v[36:51], v[52:55], v[188:191], v[36:51]
	ds_read_b128 v[52:55], v198 offset:17568
	s_waitcnt lgkmcnt(3)
	v_mfma_f32_32x32x16_bf16 v[36:51], v[56:59], v[184:187], v[36:51]
	ds_read_b128 v[56:59], v198 offset:17600
	s_waitcnt lgkmcnt(3)
	v_mfma_f32_32x32x16_bf16 v[36:51], v[60:63], v[180:183], v[36:51]
	ds_read_b128 v[60:63], v198 offset:17632
	s_waitcnt lgkmcnt(3)
	v_mfma_f32_32x32x16_bf16 v[36:51], v[64:67], v[176:179], v[36:51]
	s_waitcnt lgkmcnt(2)
	v_mfma_f32_32x32x16_bf16 v[36:51], v[52:55], v[168:171], v[36:51]
	s_waitcnt lgkmcnt(1)
	v_mfma_f32_32x32x16_bf16 v[36:51], v[56:59], v[164:167], v[36:51]
	s_waitcnt lgkmcnt(0)
	v_mfma_f32_32x32x16_bf16 v[36:51], v[60:63], v[172:175], v[36:51]
	ds_read_b128 v[52:55], v198 offset:26112
	ds_read_b128 v[68:71], v198 offset:26144
	ds_read_b128 v[72:75], v198 offset:26176
	ds_read_b128 v[76:79], v198 offset:26208
	ds_read_b128 v[80:83], v198 offset:26240
	v_or_b32_e32 v212, 0x60, v213
	s_waitcnt lgkmcnt(4)
	v_mfma_f32_32x32x16_bf16 v[52:67], v[52:55], v[116:119], 0
	s_waitcnt lgkmcnt(3)
	v_mfma_f32_32x32x16_bf16 v[52:67], v[68:71], v[188:191], v[52:67]
	ds_read_b128 v[68:71], v198 offset:26272
	s_waitcnt lgkmcnt(3)
	v_mfma_f32_32x32x16_bf16 v[52:67], v[72:75], v[184:187], v[52:67]
	ds_read_b128 v[72:75], v198 offset:26304
	s_waitcnt lgkmcnt(3)
	v_mfma_f32_32x32x16_bf16 v[52:67], v[76:79], v[180:183], v[52:67]
	ds_read_b128 v[76:79], v198 offset:26336
	s_waitcnt lgkmcnt(3)
	v_mfma_f32_32x32x16_bf16 v[52:67], v[80:83], v[176:179], v[52:67]
	s_waitcnt lgkmcnt(2)
	v_mfma_f32_32x32x16_bf16 v[52:67], v[68:71], v[168:171], v[52:67]
	s_waitcnt lgkmcnt(1)
	v_mfma_f32_32x32x16_bf16 v[52:67], v[72:75], v[164:167], v[52:67]
	s_waitcnt lgkmcnt(0)
	v_mfma_f32_32x32x16_bf16 v[52:67], v[76:79], v[172:175], v[52:67]
	ds_read_b128 v[68:71], v198 offset:34816
	ds_read_b128 v[84:87], v198 offset:34848
	ds_read_b128 v[88:91], v198 offset:34880
	ds_read_b128 v[92:95], v198 offset:34912
	ds_read_b128 v[96:99], v198 offset:34944
	s_waitcnt lgkmcnt(4)
	v_mfma_f32_32x32x16_bf16 v[68:83], v[68:71], v[116:119], 0
	s_waitcnt lgkmcnt(3)
	v_mfma_f32_32x32x16_bf16 v[68:83], v[84:87], v[188:191], v[68:83]
	ds_read_b128 v[84:87], v198 offset:34976
	s_waitcnt lgkmcnt(3)
	v_mfma_f32_32x32x16_bf16 v[68:83], v[88:91], v[184:187], v[68:83]
	ds_read_b128 v[88:91], v198 offset:35008
	s_waitcnt lgkmcnt(3)
	v_mfma_f32_32x32x16_bf16 v[68:83], v[92:95], v[180:183], v[68:83]
	ds_read_b128 v[92:95], v198 offset:35040
	s_waitcnt lgkmcnt(3)
	v_mfma_f32_32x32x16_bf16 v[68:83], v[96:99], v[176:179], v[68:83]
	s_waitcnt lgkmcnt(2)
	v_mfma_f32_32x32x16_bf16 v[68:83], v[84:87], v[168:171], v[68:83]
	s_waitcnt lgkmcnt(1)
	v_mfma_f32_32x32x16_bf16 v[68:83], v[88:91], v[164:167], v[68:83]
	s_waitcnt lgkmcnt(0)
	v_mfma_f32_32x32x16_bf16 v[68:83], v[92:95], v[172:175], v[68:83]
	ds_read_b128 v[84:87], v198 offset:43520
	ds_read_b128 v[100:103], v198 offset:43552
	ds_read_b128 v[104:107], v198 offset:43584
	ds_read_b128 v[108:111], v198 offset:43616
	ds_read_b128 v[112:115], v198 offset:43648
	s_waitcnt lgkmcnt(4)
	v_mfma_f32_32x32x16_bf16 v[84:99], v[84:87], v[116:119], 0
	s_waitcnt lgkmcnt(3)
	v_mfma_f32_32x32x16_bf16 v[84:99], v[100:103], v[188:191], v[84:99]
	ds_read_b128 v[100:103], v198 offset:43680
	s_waitcnt lgkmcnt(3)
	v_mfma_f32_32x32x16_bf16 v[84:99], v[104:107], v[184:187], v[84:99]
	ds_read_b128 v[104:107], v198 offset:43712
	s_waitcnt lgkmcnt(3)
	v_mfma_f32_32x32x16_bf16 v[84:99], v[108:111], v[180:183], v[84:99]
	ds_read_b128 v[108:111], v198 offset:43744
	s_waitcnt lgkmcnt(3)
	v_mfma_f32_32x32x16_bf16 v[84:99], v[112:115], v[176:179], v[84:99]
	s_waitcnt lgkmcnt(2)
	v_mfma_f32_32x32x16_bf16 v[84:99], v[100:103], v[168:171], v[84:99]
	s_waitcnt lgkmcnt(1)
	v_mfma_f32_32x32x16_bf16 v[84:99], v[104:107], v[164:167], v[84:99]
	s_waitcnt lgkmcnt(0)
	v_mfma_f32_32x32x16_bf16 v[84:99], v[108:111], v[172:175], v[84:99]
	ds_read_b128 v[100:103], v198 offset:52224
	ds_read_b128 v[120:123], v198 offset:52256
	ds_read_b128 v[124:127], v198 offset:52288
	ds_read_b128 v[128:131], v198 offset:52320
	s_waitcnt lgkmcnt(3)
	v_mfma_f32_32x32x16_bf16 v[100:115], v[100:103], v[116:119], 0
	s_waitcnt lgkmcnt(2)
	v_mfma_f32_32x32x16_bf16 v[100:115], v[120:123], v[188:191], v[100:115]
	ds_read_b128 v[120:123], v198 offset:52352
	s_waitcnt lgkmcnt(2)
	v_mfma_f32_32x32x16_bf16 v[100:115], v[124:127], v[184:187], v[100:115]
	ds_read_b128 v[124:127], v198 offset:52384
	s_waitcnt lgkmcnt(2)
	v_mfma_f32_32x32x16_bf16 v[100:115], v[128:131], v[180:183], v[100:115]
	ds_read_b128 v[128:131], v198 offset:52416
	s_waitcnt lgkmcnt(2)
	v_mfma_f32_32x32x16_bf16 v[100:115], v[120:123], v[176:179], v[100:115]
	ds_read_b128 v[120:123], v198 offset:52448
	s_waitcnt lgkmcnt(2)
	v_mfma_f32_32x32x16_bf16 v[100:115], v[124:127], v[168:171], v[100:115]
	s_waitcnt lgkmcnt(1)
	v_mfma_f32_32x32x16_bf16 v[100:115], v[128:131], v[164:167], v[100:115]
	s_waitcnt lgkmcnt(0)
	v_mfma_f32_32x32x16_bf16 v[100:115], v[120:123], v[172:175], v[100:115]
	ds_read_b128 v[120:123], v198 offset:60928
	ds_read_b128 v[200:203], v198 offset:60960
	s_waitcnt lgkmcnt(1)
	v_mfma_f32_32x32x16_bf16 v[116:131], v[120:123], v[116:119], 0
	s_waitcnt lgkmcnt(0)
	v_mfma_f32_32x32x16_bf16 v[116:131], v[200:203], v[188:191], v[116:131]
	ds_read_b128 v[188:191], v198 offset:60992
	s_waitcnt lgkmcnt(0)
	v_mfma_f32_32x32x16_bf16 v[116:131], v[188:191], v[184:187], v[116:131]
	ds_read_b128 v[184:187], v198 offset:61024
	s_waitcnt lgkmcnt(0)
	v_mfma_f32_32x32x16_bf16 v[116:131], v[184:187], v[180:183], v[116:131]
	ds_read_b128 v[180:183], v198 offset:61056
	s_waitcnt lgkmcnt(0)
	v_mfma_f32_32x32x16_bf16 v[116:131], v[180:183], v[176:179], v[116:131]
	ds_read_b128 v[176:179], v198 offset:61088
	s_waitcnt lgkmcnt(0)
	v_mfma_f32_32x32x16_bf16 v[116:131], v[176:179], v[168:171], v[116:131]
	ds_read_b128 v[168:171], v198 offset:61120
	s_waitcnt lgkmcnt(0)
	v_mfma_f32_32x32x16_bf16 v[116:131], v[168:171], v[164:167], v[116:131]
	ds_read_b128 v[164:167], v198 offset:61152
	s_waitcnt lgkmcnt(0)
	v_mfma_f32_32x32x16_bf16 v[116:131], v[164:167], v[172:175], v[116:131]
	v_max3_f32 v164, v4, s76, v5
	v_max3_f32 v164, v164, v6, v7
	v_max3_f32 v164, v164, v8, v9
	v_max3_f32 v164, v164, v10, v11
	v_max3_f32 v164, v164, v12, v13
	v_max3_f32 v164, v164, v14, v15
	v_max3_f32 v164, v164, v16, v17
	v_max3_f32 v164, v164, v18, v19
	v_max3_f32 v164, v164, v20, v21
	v_max3_f32 v164, v164, v22, v23
	v_max3_f32 v164, v164, v24, v25
	v_max3_f32 v164, v164, v26, v27
	v_max3_f32 v164, v164, v28, v29
	v_max3_f32 v164, v164, v30, v31
	v_max3_f32 v164, v164, v32, v33
	v_max3_f32 v164, v164, v34, v35
	v_max3_f32 v164, v164, v36, v37
	v_max3_f32 v164, v164, v38, v39
	v_max3_f32 v164, v164, v40, v41
	v_max3_f32 v164, v164, v42, v43
	v_max3_f32 v164, v164, v44, v45
	v_max3_f32 v164, v164, v46, v47
	v_max3_f32 v164, v164, v48, v49
	v_max3_f32 v164, v164, v50, v51
	v_max3_f32 v164, v164, v52, v53
	v_max3_f32 v164, v164, v54, v55
	v_max3_f32 v164, v164, v56, v57
	v_max3_f32 v164, v164, v58, v59
	v_max3_f32 v164, v164, v60, v61
	v_max3_f32 v164, v164, v62, v63
	v_max3_f32 v164, v164, v64, v65
	v_max3_f32 v164, v164, v66, v67
	v_max3_f32 v164, v164, v68, v69
	v_max3_f32 v164, v164, v70, v71
	v_max3_f32 v164, v164, v72, v73
	v_max3_f32 v164, v164, v74, v75
	v_max3_f32 v164, v164, v76, v77
	v_max3_f32 v164, v164, v78, v79
	v_max3_f32 v164, v164, v80, v81
	v_max3_f32 v164, v164, v82, v83
	v_max3_f32 v164, v164, v84, v85
	v_max3_f32 v164, v164, v86, v87
	v_max3_f32 v164, v164, v88, v89
	v_max3_f32 v164, v164, v90, v91
	v_max3_f32 v164, v164, v92, v93
	v_max3_f32 v164, v164, v94, v95
	v_max3_f32 v164, v164, v96, v97
	v_max3_f32 v164, v164, v98, v99
	v_max3_f32 v164, v164, v100, v101
	v_max3_f32 v164, v164, v102, v103
	v_max3_f32 v164, v164, v104, v105
	v_max3_f32 v164, v164, v106, v107
	v_max3_f32 v164, v164, v108, v109
	v_max3_f32 v164, v164, v110, v111
	v_max3_f32 v164, v164, v112, v113
	v_max3_f32 v164, v164, v114, v115
	v_max3_f32 v164, v164, v116, v117
	v_max3_f32 v164, v164, v118, v119
	v_max3_f32 v164, v164, v120, v121
	v_max3_f32 v164, v164, v122, v123
	v_max3_f32 v164, v164, v124, v125
	v_max3_f32 v164, v164, v126, v127
	v_max3_f32 v164, v164, v128, v129
	v_max3_f32 v164, v164, v130, v131
	ds_bpermute_b32 v165, v197, v164
	s_waitcnt lgkmcnt(0)
	s_barrier
	v_max_f32_e32 v165, v165, v165
	v_max_f32_e32 v216, v164, v165
	v_sub_f32_e32 v10, v10, v216
	v_exp_f32_e32 v164, v10
	v_sub_f32_e32 v10, v11, v216
	v_exp_f32_e32 v165, v10
	v_sub_f32_e32 v10, v12, v216
	v_exp_f32_e32 v166, v10
	v_sub_f32_e32 v10, v13, v216
	v_exp_f32_e32 v167, v10
	v_sub_f32_e32 v10, v14, v216
	v_exp_f32_e32 v168, v10
	v_sub_f32_e32 v10, v15, v216
	v_exp_f32_e32 v169, v10
	v_sub_f32_e32 v10, v16, v216
	v_exp_f32_e32 v170, v10
	v_sub_f32_e32 v10, v17, v216
	v_sub_f32_e32 v16, v26, v216
	v_exp_f32_e32 v171, v10
	v_sub_f32_e32 v10, v18, v216
	v_exp_f32_e32 v18, v16
	v_sub_f32_e32 v16, v27, v216
	v_exp_f32_e32 v172, v10
	v_sub_f32_e32 v10, v19, v216
	v_exp_f32_e32 v19, v16
	v_sub_f32_e32 v16, v28, v216
	v_exp_f32_e32 v28, v16
	v_sub_f32_e32 v16, v29, v216
	v_exp_f32_e32 v29, v16
	v_sub_f32_e32 v16, v30, v216
	v_exp_f32_e32 v30, v16
	v_sub_f32_e32 v16, v31, v216
	v_exp_f32_e32 v31, v16
	v_sub_f32_e32 v16, v32, v216
	v_exp_f32_e32 v32, v16
	v_sub_f32_e32 v16, v33, v216
	v_exp_f32_e32 v33, v16
	v_sub_f32_e32 v16, v34, v216
	v_exp_f32_e32 v173, v10
	v_sub_f32_e32 v10, v20, v216
	v_exp_f32_e32 v34, v16
	v_sub_f32_e32 v16, v35, v216
	v_sub_f32_e32 v20, v38, v216
	v_exp_f32_e32 v35, v16
	v_sub_f32_e32 v16, v36, v216
	v_exp_f32_e32 v36, v20
	v_sub_f32_e32 v20, v39, v216
	v_sub_f32_e32 v17, v37, v216
	v_exp_f32_e32 v37, v20
	v_sub_f32_e32 v20, v40, v216
	v_exp_f32_e32 v38, v20
	v_sub_f32_e32 v20, v41, v216
	v_exp_f32_e32 v39, v20
	v_sub_f32_e32 v20, v42, v216
	v_exp_f32_e32 v40, v20
	v_sub_f32_e32 v20, v43, v216
	v_exp_f32_e32 v41, v20
	v_sub_f32_e32 v20, v44, v216
	v_exp_f32_e32 v42, v20
	v_sub_f32_e32 v20, v45, v216
	v_exp_f32_e32 v43, v20
	v_sub_f32_e32 v20, v46, v216
	v_exp_f32_e32 v174, v20
	v_sub_f32_e32 v20, v47, v216
	v_exp_f32_e32 v175, v20
	v_sub_f32_e32 v20, v48, v216
	v_exp_f32_e32 v176, v20
	v_sub_f32_e32 v20, v49, v216
	v_exp_f32_e32 v177, v20
	v_sub_f32_e32 v20, v50, v216
	v_exp_f32_e32 v178, v20
	v_sub_f32_e32 v20, v51, v216
	v_exp_f32_e32 v179, v20
	v_sub_f32_e32 v20, v52, v216
	v_exp_f32_e32 v44, v20
	v_sub_f32_e32 v20, v53, v216
	v_exp_f32_e32 v45, v20
	v_sub_f32_e32 v20, v54, v216
	v_exp_f32_e32 v46, v20
	v_sub_f32_e32 v20, v55, v216
	v_exp_f32_e32 v47, v20
	v_sub_f32_e32 v20, v56, v216
	v_exp_f32_e32 v48, v20
	v_sub_f32_e32 v20, v57, v216
	v_exp_f32_e32 v49, v20
	v_sub_f32_e32 v20, v58, v216
	v_exp_f32_e32 v50, v20
	v_sub_f32_e32 v20, v59, v216
	v_exp_f32_e32 v51, v20
	v_sub_f32_e32 v20, v60, v216
	v_exp_f32_e32 v56, v20
	v_sub_f32_e32 v20, v61, v216
	v_exp_f32_e32 v57, v20
	v_sub_f32_e32 v20, v62, v216
	v_exp_f32_e32 v60, v20
	v_sub_f32_e32 v20, v63, v216
	v_exp_f32_e32 v61, v20
	v_sub_f32_e32 v20, v64, v216
	v_exp_f32_e32 v180, v20
	v_sub_f32_e32 v20, v65, v216
	v_exp_f32_e32 v181, v20
	v_sub_f32_e32 v20, v66, v216
	v_exp_f32_e32 v182, v20
	v_sub_f32_e32 v20, v67, v216
	v_exp_f32_e32 v183, v20
	v_sub_f32_e32 v20, v68, v216
	v_exp_f32_e32 v52, v20
	v_sub_f32_e32 v20, v69, v216
	v_exp_f32_e32 v53, v20
	v_sub_f32_e32 v20, v70, v216
	v_exp_f32_e32 v54, v20
	v_sub_f32_e32 v20, v71, v216
	v_exp_f32_e32 v55, v20
	v_sub_f32_e32 v20, v72, v216
	v_exp_f32_e32 v58, v20
	v_sub_f32_e32 v20, v73, v216
	v_exp_f32_e32 v59, v20
	v_sub_f32_e32 v20, v74, v216
	v_exp_f32_e32 v64, v20
	v_sub_f32_e32 v20, v75, v216
	v_exp_f32_e32 v65, v20
	v_sub_f32_e32 v20, v76, v216
	v_exp_f32_e32 v68, v20
	v_sub_f32_e32 v20, v77, v216
	v_exp_f32_e32 v69, v20
	v_sub_f32_e32 v20, v78, v216
	v_exp_f32_e32 v72, v20
	v_sub_f32_e32 v20, v79, v216
	v_exp_f32_e32 v73, v20
	v_sub_f32_e32 v20, v80, v216
	v_exp_f32_e32 v186, v20
	v_sub_f32_e32 v20, v81, v216
	v_exp_f32_e32 v187, v20
	v_sub_f32_e32 v20, v82, v216
	v_exp_f32_e32 v190, v20
	v_sub_f32_e32 v20, v83, v216
	v_exp_f32_e32 v191, v20
	v_sub_f32_e32 v20, v84, v216
	v_exp_f32_e32 v62, v20
	v_sub_f32_e32 v20, v85, v216
	v_exp_f32_e32 v63, v20
	v_sub_f32_e32 v20, v86, v216
	v_exp_f32_e32 v66, v20
	v_sub_f32_e32 v20, v87, v216
	v_exp_f32_e32 v67, v20
	v_sub_f32_e32 v20, v88, v216
	v_exp_f32_e32 v70, v20
	v_sub_f32_e32 v20, v89, v216
	v_exp_f32_e32 v71, v20
	v_sub_f32_e32 v20, v90, v216
	v_exp_f32_e32 v184, v20
	v_sub_f32_e32 v20, v91, v216
	v_exp_f32_e32 v185, v20
	v_sub_f32_e32 v20, v92, v216
	v_exp_f32_e32 v188, v20
	v_sub_f32_e32 v20, v93, v216
	v_exp_f32_e32 v189, v20
	v_sub_f32_e32 v20, v94, v216
	v_exp_f32_e32 v198, v20
	v_sub_f32_e32 v20, v95, v216
	v_exp_f32_e32 v199, v20
	v_sub_f32_e32 v20, v96, v216
	v_exp_f32_e32 v200, v20
	v_sub_f32_e32 v20, v97, v216
	v_exp_f32_e32 v201, v20
	v_sub_f32_e32 v20, v98, v216
	v_exp_f32_e32 v202, v20
	v_sub_f32_e32 v20, v99, v216
	v_exp_f32_e32 v203, v20
	v_sub_f32_e32 v20, v100, v216
	v_exp_f32_e32 v74, v20
	v_sub_f32_e32 v20, v101, v216
	v_exp_f32_e32 v75, v20
	v_sub_f32_e32 v20, v102, v216
	v_exp_f32_e32 v92, v20
	v_sub_f32_e32 v20, v103, v216
	v_exp_f32_e32 v93, v20
	v_sub_f32_e32 v20, v104, v216
	v_exp_f32_e32 v94, v20
	v_sub_f32_e32 v20, v105, v216
	v_exp_f32_e32 v95, v20
	v_sub_f32_e32 v20, v106, v216
	v_exp_f32_e32 v96, v20
	v_sub_f32_e32 v20, v107, v216
	v_exp_f32_e32 v97, v20
	v_sub_f32_e32 v20, v108, v216
	v_exp_f32_e32 v98, v20
	v_sub_f32_e32 v20, v109, v216
	v_exp_f32_e32 v99, v20
	v_sub_f32_e32 v20, v110, v216
	v_exp_f32_e32 v100, v20
	v_sub_f32_e32 v20, v111, v216
	v_exp_f32_e32 v101, v20
	v_sub_f32_e32 v20, v112, v216
	v_exp_f32_e32 v102, v20
	v_sub_f32_e32 v20, v113, v216
	v_exp_f32_e32 v103, v20
	v_sub_f32_e32 v20, v114, v216
	v_exp_f32_e32 v104, v20
	v_sub_f32_e32 v20, v115, v216
	v_exp_f32_e32 v105, v20
	v_sub_f32_e32 v20, v116, v216
	v_exp_f32_e32 v76, v20
	v_sub_f32_e32 v20, v117, v216
	v_exp_f32_e32 v77, v20
	v_sub_f32_e32 v20, v118, v216
	v_exp_f32_e32 v80, v20
	v_sub_f32_e32 v20, v119, v216
	v_exp_f32_e32 v81, v20
	v_sub_f32_e32 v20, v120, v216
	v_exp_f32_e32 v84, v20
	v_sub_f32_e32 v20, v121, v216
	v_exp_f32_e32 v85, v20
	v_sub_f32_e32 v20, v122, v216
	v_exp_f32_e32 v88, v20
	v_sub_f32_e32 v20, v123, v216
	v_exp_f32_e32 v89, v20
	v_sub_f32_e32 v20, v124, v216
	v_exp_f32_e32 v78, v20
	v_sub_f32_e32 v20, v125, v216
	v_exp_f32_e32 v79, v20
	v_sub_f32_e32 v20, v126, v216
	v_sub_f32_e32 v4, v4, v216
	v_exp_f32_e32 v82, v20
	v_sub_f32_e32 v20, v127, v216
	v_sub_f32_e32 v5, v5, v216
	v_exp_f32_e32 v4, v4
	v_exp_f32_e32 v83, v20
	v_sub_f32_e32 v20, v128, v216
	v_sub_f32_e32 v6, v6, v216
	v_exp_f32_e32 v5, v5
	v_exp_f32_e32 v86, v20
	v_sub_f32_e32 v20, v129, v216
	v_exp_f32_e32 v6, v6
	v_sub_f32_e32 v7, v7, v216
	v_exp_f32_e32 v87, v20
	v_sub_f32_e32 v20, v130, v216
	v_exp_f32_e32 v7, v7
	v_sub_f32_e32 v8, v8, v216
	v_exp_f32_e32 v90, v20
	v_sub_f32_e32 v20, v131, v216
	v_exp_f32_e32 v8, v8
	v_sub_f32_e32 v9, v9, v216
	v_exp_f32_e32 v91, v20
	v_add_f32_e32 v20, 0, v4
	v_exp_f32_e32 v9, v9
	v_add_f32_e32 v20, v5, v20
	v_add_f32_e32 v20, v6, v20
	v_add_f32_e32 v20, v7, v20
	v_add_f32_e32 v20, v8, v20
	v_add_f32_e32 v20, v9, v20
	v_add_f32_e32 v20, v164, v20
	v_add_f32_e32 v20, v165, v20
	v_add_f32_e32 v20, v166, v20
	v_add_f32_e32 v20, v167, v20
	v_add_f32_e32 v20, v168, v20
	v_add_f32_e32 v20, v169, v20
	v_exp_f32_e32 v10, v10
	v_sub_f32_e32 v11, v21, v216
	v_add_f32_e32 v20, v170, v20
	v_exp_f32_e32 v11, v11
	v_sub_f32_e32 v12, v22, v216
	v_add_f32_e32 v20, v171, v20
	v_exp_f32_e32 v12, v12
	v_sub_f32_e32 v13, v23, v216
	v_add_f32_e32 v20, v172, v20
	v_exp_f32_e32 v13, v13
	v_sub_f32_e32 v14, v24, v216
	v_add_f32_e32 v20, v173, v20
	v_exp_f32_e32 v14, v14
	v_sub_f32_e32 v15, v25, v216
	v_add_f32_e32 v20, v10, v20
	v_exp_f32_e32 v15, v15
	v_add_f32_e32 v20, v11, v20
	v_add_f32_e32 v20, v12, v20
	v_add_f32_e32 v20, v13, v20
	v_add_f32_e32 v20, v14, v20
	v_add_f32_e32 v20, v15, v20
	v_add_f32_e32 v20, v18, v20
	v_add_f32_e32 v20, v19, v20
	v_add_f32_e32 v20, v28, v20
	v_add_f32_e32 v20, v29, v20
	v_add_f32_e32 v20, v30, v20
	v_add_f32_e32 v20, v31, v20
	v_exp_f32_e32 v16, v16
	v_add_f32_e32 v20, v32, v20
	v_exp_f32_e32 v17, v17
	v_add_f32_e32 v20, v33, v20
	v_add_f32_e32 v20, v34, v20
	v_add_f32_e32 v20, v35, v20
	v_add_f32_e32 v20, v16, v20
	v_add_f32_e32 v20, v17, v20
	v_add_f32_e32 v20, v36, v20
	v_add_f32_e32 v20, v37, v20
	v_add_f32_e32 v20, v38, v20
	v_add_f32_e32 v20, v39, v20
	v_add_f32_e32 v20, v40, v20
	v_add_f32_e32 v20, v41, v20
	v_add_f32_e32 v20, v42, v20
	v_add_f32_e32 v20, v43, v20
	v_add_f32_e32 v20, v174, v20
	v_add_f32_e32 v20, v175, v20
	v_add_f32_e32 v20, v176, v20
	v_add_f32_e32 v20, v177, v20
	v_add_f32_e32 v20, v178, v20
	v_add_f32_e32 v20, v179, v20
	v_add_f32_e32 v20, v44, v20
	v_add_f32_e32 v20, v45, v20
	v_add_f32_e32 v20, v46, v20
	v_add_f32_e32 v20, v47, v20
	v_add_f32_e32 v20, v48, v20
	v_add_f32_e32 v20, v49, v20
	v_add_f32_e32 v20, v50, v20
	v_add_f32_e32 v20, v51, v20
	v_add_f32_e32 v20, v56, v20
	v_add_f32_e32 v20, v57, v20
	v_add_f32_e32 v20, v60, v20
	v_add_f32_e32 v20, v61, v20
	v_add_f32_e32 v20, v180, v20
	v_add_f32_e32 v20, v181, v20
	v_add_f32_e32 v20, v182, v20
	v_add_f32_e32 v20, v183, v20
	v_add_f32_e32 v20, v52, v20
	v_add_f32_e32 v20, v53, v20
	v_add_f32_e32 v20, v54, v20
	v_add_f32_e32 v20, v55, v20
	v_add_f32_e32 v20, v58, v20
	v_add_f32_e32 v20, v59, v20
	v_add_f32_e32 v20, v64, v20
	v_add_f32_e32 v20, v65, v20
	v_add_f32_e32 v20, v68, v20
	v_add_f32_e32 v20, v69, v20
	v_add_f32_e32 v20, v72, v20
	v_add_f32_e32 v20, v73, v20
	v_add_f32_e32 v20, v186, v20
	v_add_f32_e32 v20, v187, v20
	v_add_f32_e32 v20, v190, v20
	v_add_f32_e32 v20, v191, v20
	v_add_f32_e32 v20, v62, v20
	v_add_f32_e32 v20, v63, v20
	v_add_f32_e32 v20, v66, v20
	v_add_f32_e32 v20, v67, v20
	v_add_f32_e32 v20, v70, v20
	v_add_f32_e32 v20, v71, v20
	v_add_f32_e32 v20, v184, v20
	v_add_f32_e32 v20, v185, v20
	v_add_f32_e32 v20, v188, v20
	v_add_f32_e32 v20, v189, v20
	v_add_f32_e32 v20, v198, v20
	v_add_f32_e32 v20, v199, v20
	v_add_f32_e32 v20, v200, v20
	v_add_f32_e32 v20, v201, v20
	v_add_f32_e32 v20, v202, v20
	v_add_f32_e32 v20, v203, v20
	v_add_f32_e32 v20, v74, v20
	v_add_f32_e32 v20, v75, v20
	v_add_f32_e32 v20, v92, v20
	v_add_f32_e32 v20, v93, v20
	v_add_f32_e32 v20, v94, v20
	v_add_f32_e32 v20, v95, v20
	v_add_f32_e32 v20, v96, v20
	v_add_f32_e32 v20, v97, v20
	v_add_f32_e32 v20, v98, v20
	v_add_f32_e32 v20, v99, v20
	v_add_f32_e32 v20, v100, v20
	v_add_f32_e32 v20, v101, v20
	v_add_f32_e32 v20, v102, v20
	v_add_f32_e32 v20, v103, v20
	v_add_f32_e32 v20, v104, v20
	v_add_f32_e32 v20, v105, v20
	v_add_f32_e32 v20, v76, v20
	v_add_f32_e32 v20, v77, v20
	v_add_f32_e32 v20, v80, v20
	v_add_f32_e32 v20, v81, v20
	v_add_f32_e32 v20, v84, v20
	v_add_f32_e32 v20, v85, v20
	v_add_f32_e32 v20, v88, v20
	v_add_f32_e32 v20, v89, v20
	v_add_f32_e32 v20, v78, v20
	v_add_f32_e32 v20, v79, v20
	v_add_f32_e32 v20, v82, v20
	v_add_f32_e32 v20, v83, v20
	v_add_f32_e32 v20, v86, v20
	v_add_f32_e32 v20, v87, v20
	v_add_f32_e32 v20, v90, v20
	v_add_f32_e32 v20, v91, v20
	ds_bpermute_b32 v21, v197, v20
	s_waitcnt lgkmcnt(0)
	v_add_f32_e32 v20, v20, v21
	v_div_scale_f32 v21, s[44:45], v20, v20, 1.0
	v_rcp_f32_e32 v22, v21
	s_nop 0
	v_fma_f32 v23, -v21, v22, 1.0
	v_fmac_f32_e32 v22, v23, v22
	v_div_scale_f32 v23, vcc, 1.0, v20, 1.0
	v_mul_f32_e32 v24, v23, v22
	v_fma_f32 v25, -v21, v24, v23
	v_fmac_f32_e32 v24, v25, v22
	v_fma_f32 v21, -v21, v24, v23
	v_div_fmas_f32 v21, v21, v22, v24
	v_div_fixup_f32 v106, v21, v20, 1.0
	v_pk_mul_f32 v[6:7], v[6:7], v[106:107] op_sel_hi:[1,0]
	v_pk_mul_f32 v[4:5], v[4:5], v[106:107] op_sel_hi:[1,0]
	v_pk_mul_f32 v[8:9], v[8:9], v[106:107] op_sel_hi:[1,0]
	v_cvt_pk_bf16_f32 v21, v6, v7
	v_pk_mul_f32 v[6:7], v[12:13], v[106:107] op_sel_hi:[1,0]
	v_pk_mul_f32 v[24:25], v[164:165], v[106:107] op_sel_hi:[1,0]
	v_pk_mul_f32 v[108:109], v[168:169], v[106:107] op_sel_hi:[1,0]
	v_cvt_pk_bf16_f32 v20, v4, v5
	v_cvt_pk_bf16_f32 v22, v8, v9
	v_pk_mul_f32 v[4:5], v[10:11], v[106:107] op_sel_hi:[1,0]
	v_pk_mul_f32 v[8:9], v[14:15], v[106:107] op_sel_hi:[1,0]
	v_pk_mul_f32 v[10:11], v[18:19], v[106:107] op_sel_hi:[1,0]
	v_pk_mul_f32 v[18:19], v[32:33], v[106:107] op_sel_hi:[1,0]
	v_cvt_pk_bf16_f32 v33, v6, v7
	v_pk_mul_f32 v[6:7], v[36:37], v[106:107] op_sel_hi:[1,0]
	v_cvt_pk_bf16_f32 v23, v24, v25
	v_cvt_pk_bf16_f32 v25, v108, v109
	v_pk_mul_f32 v[108:109], v[34:35], v[106:107] op_sel_hi:[1,0]
	v_cvt_pk_bf16_f32 v32, v4, v5
	v_cvt_pk_bf16_f32 v34, v8, v9
	v_pk_mul_f32 v[4:5], v[16:17], v[106:107] op_sel_hi:[1,0]
	v_pk_mul_f32 v[8:9], v[38:39], v[106:107] op_sel_hi:[1,0]
	v_cvt_pk_bf16_f32 v37, v6, v7
	v_pk_mul_f32 v[6:7], v[46:47], v[106:107] op_sel_hi:[1,0]
	v_cvt_pk_bf16_f32 v35, v10, v11
	v_pk_mul_f32 v[10:11], v[40:41], v[106:107] op_sel_hi:[1,0]
	v_cvt_pk_bf16_f32 v36, v4, v5
	v_cvt_pk_bf16_f32 v38, v8, v9
	v_pk_mul_f32 v[4:5], v[44:45], v[106:107] op_sel_hi:[1,0]
	v_pk_mul_f32 v[8:9], v[48:49], v[106:107] op_sel_hi:[1,0]
	v_cvt_pk_bf16_f32 v49, v6, v7
	v_pk_mul_f32 v[6:7], v[54:55], v[106:107] op_sel_hi:[1,0]
	v_pk_mul_f32 v[12:13], v[28:29], v[106:107] op_sel_hi:[1,0]
	v_cvt_pk_bf16_f32 v39, v10, v11
	v_pk_mul_f32 v[10:11], v[50:51], v[106:107] op_sel_hi:[1,0]
	v_cvt_pk_bf16_f32 v48, v4, v5
	v_pk_mul_f32 v[4:5], v[52:53], v[106:107] op_sel_hi:[1,0]
	v_cvt_pk_bf16_f32 v53, v6, v7
	v_pk_mul_f32 v[6:7], v[66:67], v[106:107] op_sel_hi:[1,0]
	v_cvt_pk_bf16_f32 v28, v12, v13
	v_pk_mul_f32 v[12:13], v[42:43], v[106:107] op_sel_hi:[1,0]
	v_cvt_pk_bf16_f32 v51, v10, v11
	v_pk_mul_f32 v[10:11], v[64:65], v[106:107] op_sel_hi:[1,0]
	v_cvt_pk_bf16_f32 v52, v4, v5
	v_pk_mul_f32 v[4:5], v[62:63], v[106:107] op_sel_hi:[1,0]
	v_cvt_pk_bf16_f32 v65, v6, v7
	v_pk_mul_f32 v[6:7], v[92:93], v[106:107] op_sel_hi:[1,0]
	v_add_u32_e32 v92, s11, v215
	v_pk_mul_f32 v[14:15], v[30:31], v[106:107] op_sel_hi:[1,0]
	v_cvt_pk_bf16_f32 v40, v12, v13
	v_pk_mul_f32 v[12:13], v[56:57], v[106:107] op_sel_hi:[1,0]
	v_cvt_pk_bf16_f32 v64, v4, v5
	v_pk_mul_f32 v[4:5], v[74:75], v[106:107] op_sel_hi:[1,0]
	v_mad_u32_u24 v93, v213, s8, v92
	v_cvt_pk_bf16_f32 v29, v14, v15
	v_cvt_pk_bf16_f32 v30, v18, v19
	v_pk_mul_f32 v[14:15], v[174:175], v[106:107] op_sel_hi:[1,0]
	v_pk_mul_f32 v[16:17], v[176:177], v[106:107] op_sel_hi:[1,0]
	v_pk_mul_f32 v[18:19], v[178:179], v[106:107] op_sel_hi:[1,0]
	v_cvt_pk_bf16_f32 v44, v12, v13
	v_pk_mul_f32 v[12:13], v[68:69], v[106:107] op_sel_hi:[1,0]
	v_cvt_pk_bf16_f32 v68, v4, v5
	v_cvt_pk_bf16_f32 v69, v6, v7
	ds_read2_b64 v[4:7], v93 offset1:2
	v_cvt_pk_bf16_f32 v41, v14, v15
	v_cvt_pk_bf16_f32 v42, v16, v17
	v_cvt_pk_bf16_f32 v43, v18, v19
	v_pk_mul_f32 v[14:15], v[60:61], v[106:107] op_sel_hi:[1,0]
	v_pk_mul_f32 v[16:17], v[180:181], v[106:107] op_sel_hi:[1,0]
	v_pk_mul_f32 v[18:19], v[182:183], v[106:107] op_sel_hi:[1,0]
	v_cvt_pk_bf16_f32 v50, v8, v9
	v_cvt_pk_bf16_f32 v45, v14, v15
	v_cvt_pk_bf16_f32 v46, v16, v17
	v_cvt_pk_bf16_f32 v47, v18, v19
	v_pk_mul_f32 v[8:9], v[58:59], v[106:107] op_sel_hi:[1,0]
	v_pk_mul_f32 v[14:15], v[72:73], v[106:107] op_sel_hi:[1,0]
	v_pk_mul_f32 v[16:17], v[186:187], v[106:107] op_sel_hi:[1,0]
	v_pk_mul_f32 v[18:19], v[190:191], v[106:107] op_sel_hi:[1,0]
	v_cvt_pk_bf16_f32 v54, v8, v9
	v_cvt_pk_bf16_f32 v55, v10, v11
	v_cvt_pk_bf16_f32 v56, v12, v13
	v_cvt_pk_bf16_f32 v57, v14, v15
	v_cvt_pk_bf16_f32 v58, v16, v17
	v_cvt_pk_bf16_f32 v59, v18, v19
	v_pk_mul_f32 v[8:9], v[70:71], v[106:107] op_sel_hi:[1,0]
	v_pk_mul_f32 v[10:11], v[184:185], v[106:107] op_sel_hi:[1,0]
	v_pk_mul_f32 v[12:13], v[188:189], v[106:107] op_sel_hi:[1,0]
	v_pk_mul_f32 v[14:15], v[198:199], v[106:107] op_sel_hi:[1,0]
	v_pk_mul_f32 v[16:17], v[200:201], v[106:107] op_sel_hi:[1,0]
	v_pk_mul_f32 v[18:19], v[202:203], v[106:107] op_sel_hi:[1,0]
	v_cvt_pk_bf16_f32 v66, v8, v9
	v_cvt_pk_bf16_f32 v67, v10, v11
	v_cvt_pk_bf16_f32 v60, v12, v13
	v_cvt_pk_bf16_f32 v61, v14, v15
	v_cvt_pk_bf16_f32 v62, v16, v17
	v_cvt_pk_bf16_f32 v63, v18, v19
	v_pk_mul_f32 v[8:9], v[94:95], v[106:107] op_sel_hi:[1,0]
	v_pk_mul_f32 v[10:11], v[96:97], v[106:107] op_sel_hi:[1,0]
	v_pk_mul_f32 v[12:13], v[98:99], v[106:107] op_sel_hi:[1,0]
	v_pk_mul_f32 v[14:15], v[100:101], v[106:107] op_sel_hi:[1,0]
	v_pk_mul_f32 v[16:17], v[102:103], v[106:107] op_sel_hi:[1,0]
	v_pk_mul_f32 v[18:19], v[104:105], v[106:107] op_sel_hi:[1,0]
	v_cvt_pk_bf16_f32 v70, v8, v9
	v_cvt_pk_bf16_f32 v71, v10, v11
	v_cvt_pk_bf16_f32 v72, v12, v13
	v_cvt_pk_bf16_f32 v73, v14, v15
	v_cvt_pk_bf16_f32 v74, v16, v17
	v_cvt_pk_bf16_f32 v75, v18, v19
	s_waitcnt lgkmcnt(0)
	v_mfma_f32_32x32x16_bf16 v[4:19], v[20:23], v[4:7], 0
	v_mul_f32_e64 v26, v166, v106
	v_mul_f32_e64 v27, v167, v106
	v_mul_f32_e64 v110, v170, v106
	v_mul_f32_e64 v111, v171, v106
	v_mul_f32_e64 v112, v172, v106
	v_mul_f32_e64 v113, v173, v106
	v_cvt_pk_bf16_f32 v24, v26, v27
	v_cvt_pk_bf16_f32 v26, v110, v111
	v_cvt_pk_bf16_f32 v27, v112, v113
	v_pk_mul_f32 v[94:95], v[80:81], v[106:107] op_sel_hi:[1,0]
	v_pk_mul_f32 v[96:97], v[78:79], v[106:107] op_sel_hi:[1,0]
	ds_read2_b64 v[78:81], v93 offset0:4 offset1:6
	s_waitcnt lgkmcnt(0)
	v_mfma_f32_32x32x16_bf16 v[4:19], v[24:27], v[78:81], v[4:19]
	v_mul_f32_e64 v84, v84, v106
	v_mul_f32_e64 v85, v85, v106
	v_mul_f32_e64 v98, v86, v106
	v_mul_f32_e64 v99, v87, v106
	v_cvt_pk_bf16_f32 v78, v84, v85
	ds_read2_b64 v[84:87], v93 offset0:8 offset1:10
	v_pk_mul_f32 v[88:89], v[88:89], v[106:107] op_sel_hi:[1,0]
	v_cvt_pk_bf16_f32 v31, v108, v109
	v_cvt_pk_bf16_f32 v79, v88, v89
	s_waitcnt lgkmcnt(0)
	v_mfma_f32_32x32x16_bf16 v[4:19], v[32:35], v[84:87], v[4:19]
	ds_read2_b64 v[86:89], v93 offset0:12 offset1:14
	v_lshrrev_b32_e32 v84, 3, v211
	v_and_b32_e32 v84, 4, v84
	v_lshlrev_b32_e32 v85, 1, v211
	v_mul_f32_e64 v76, v76, v106
	v_mul_f32_e64 v77, v77, v106
	v_pk_mul_f32 v[82:83], v[82:83], v[106:107] op_sel_hi:[1,0]
	v_pk_mul_f32 v[90:91], v[90:91], v[106:107] op_sel_hi:[1,0]
	v_mul_u32_u24_e32 v84, 0x110, v84
	v_and_b32_e32 v85, 62, v85
	v_cvt_pk_bf16_f32 v76, v76, v77
	v_cvt_pk_bf16_f32 v77, v94, v95
	v_cvt_pk_bf16_f32 v80, v96, v97
	v_cvt_pk_bf16_f32 v81, v82, v83
	v_cvt_pk_bf16_f32 v82, v98, v99
	v_cvt_pk_bf16_f32 v83, v90, v91
	v_add3_u32 v84, s61, v84, v85
	s_waitcnt lgkmcnt(0)
	v_mfma_f32_32x32x16_bf16 v[4:19], v[28:31], v[86:89], v[4:19]
	ds_read2_b64 v[86:89], v93 offset0:16 offset1:18
	s_waitcnt lgkmcnt(0)
	v_mfma_f32_32x32x16_bf16 v[4:19], v[36:39], v[86:89], v[4:19]
	ds_read2_b64 v[86:89], v93 offset0:20 offset1:22
	s_waitcnt lgkmcnt(0)
	v_mfma_f32_32x32x16_bf16 v[4:19], v[40:43], v[86:89], v[4:19]
	ds_read2_b64 v[86:89], v93 offset0:24 offset1:26
	s_waitcnt lgkmcnt(0)
	v_mfma_f32_32x32x16_bf16 v[4:19], v[48:51], v[86:89], v[4:19]
	ds_read2_b64 v[86:89], v93 offset0:28 offset1:30
	s_waitcnt lgkmcnt(0)
	v_mfma_f32_32x32x16_bf16 v[4:19], v[44:47], v[86:89], v[4:19]
	ds_read2_b64 v[86:89], v93 offset0:32 offset1:34
	s_waitcnt lgkmcnt(0)
	v_mfma_f32_32x32x16_bf16 v[4:19], v[52:55], v[86:89], v[4:19]
	ds_read2_b64 v[86:89], v93 offset0:36 offset1:38
	s_waitcnt lgkmcnt(0)
	v_mfma_f32_32x32x16_bf16 v[4:19], v[56:59], v[86:89], v[4:19]
	ds_read2_b64 v[86:89], v93 offset0:40 offset1:42
	s_waitcnt lgkmcnt(0)
	v_mfma_f32_32x32x16_bf16 v[4:19], v[64:67], v[86:89], v[4:19]
	ds_read2_b64 v[86:89], v93 offset0:44 offset1:46
	s_waitcnt lgkmcnt(0)
	v_mfma_f32_32x32x16_bf16 v[4:19], v[60:63], v[86:89], v[4:19]
	ds_read2_b64 v[86:89], v93 offset0:48 offset1:50
	s_waitcnt lgkmcnt(0)
	v_mfma_f32_32x32x16_bf16 v[4:19], v[68:71], v[86:89], v[4:19]
	ds_read2_b64 v[86:89], v93 offset0:52 offset1:54
	s_waitcnt lgkmcnt(0)
	v_mfma_f32_32x32x16_bf16 v[4:19], v[72:75], v[86:89], v[4:19]
	ds_read2_b64 v[86:89], v93 offset0:56 offset1:58
	s_waitcnt lgkmcnt(0)
	v_mfma_f32_32x32x16_bf16 v[4:19], v[76:79], v[86:89], v[4:19]
	ds_read2_b64 v[86:89], v93 offset0:60 offset1:62
	s_waitcnt lgkmcnt(0)
	v_mfma_f32_32x32x16_bf16 v[4:19], v[80:83], v[86:89], v[4:19]
	s_nop 11
	v_cvt_pk_bf16_f32 v4, v4, v5
	ds_write_b16 v84, v4
	ds_write_b16_d16_hi v84, v4 offset:272
	v_cvt_pk_bf16_f32 v4, v6, v7
	ds_write_b16 v84, v4 offset:544
	ds_write_b16_d16_hi v84, v4 offset:816
	v_cvt_pk_bf16_f32 v4, v8, v9
	ds_write_b16 v84, v4 offset:2176
	ds_write_b16_d16_hi v84, v4 offset:2448
	v_cvt_pk_bf16_f32 v4, v10, v11
	ds_write_b16 v84, v4 offset:2720
	ds_write_b16_d16_hi v84, v4 offset:2992
	v_cvt_pk_bf16_f32 v4, v12, v13
	ds_write_b16 v84, v4 offset:4352
	ds_write_b16_d16_hi v84, v4 offset:4624
	v_cvt_pk_bf16_f32 v4, v14, v15
	ds_write_b16 v84, v4 offset:4896
	ds_write_b16_d16_hi v84, v4 offset:5168
	v_cvt_pk_bf16_f32 v4, v16, v17
	ds_write_b16 v84, v4 offset:6528
	ds_write_b16_d16_hi v84, v4 offset:6800
	v_cvt_pk_bf16_f32 v4, v18, v19
	ds_write_b16 v84, v4 offset:7072
	ds_write_b16_d16_hi v84, v4 offset:7344
	v_add_u32_e32 v85, 0x4000, v93
	ds_read2_b64 v[4:7], v85 offset0:32 offset1:34
	ds_read2_b64 v[86:89], v85 offset0:36 offset1:38
	ds_read2_b64 v[94:97], v85 offset0:40 offset1:42
	ds_read2_b64 v[98:101], v85 offset0:44 offset1:46
	ds_read2_b64 v[102:105], v85 offset0:48 offset1:50
	s_waitcnt lgkmcnt(4)
	v_mfma_f32_32x32x16_bf16 v[4:19], v[20:23], v[4:7], 0
	s_waitcnt lgkmcnt(3)
	v_mfma_f32_32x32x16_bf16 v[4:19], v[24:27], v[86:89], v[4:19]
	ds_read2_b64 v[86:89], v85 offset0:52 offset1:54
	s_waitcnt lgkmcnt(3)
	v_mfma_f32_32x32x16_bf16 v[4:19], v[32:35], v[94:97], v[4:19]
	ds_read2_b64 v[94:97], v85 offset0:56 offset1:58
	s_waitcnt lgkmcnt(3)
	v_mfma_f32_32x32x16_bf16 v[4:19], v[28:31], v[98:101], v[4:19]
	ds_read2_b64 v[98:101], v85 offset0:60 offset1:62
	s_waitcnt lgkmcnt(3)
	v_mfma_f32_32x32x16_bf16 v[4:19], v[36:39], v[102:105], v[4:19]
	ds_read2_b64 v[102:105], v85 offset0:64 offset1:66
	s_waitcnt lgkmcnt(3)
	v_mfma_f32_32x32x16_bf16 v[4:19], v[40:43], v[86:89], v[4:19]
	ds_read2_b64 v[86:89], v85 offset0:68 offset1:70
	s_waitcnt lgkmcnt(3)
	v_mfma_f32_32x32x16_bf16 v[4:19], v[48:51], v[94:97], v[4:19]
	ds_read2_b64 v[94:97], v85 offset0:72 offset1:74
	s_waitcnt lgkmcnt(3)
	v_mfma_f32_32x32x16_bf16 v[4:19], v[44:47], v[98:101], v[4:19]
	ds_read2_b64 v[98:101], v85 offset0:76 offset1:78
	s_waitcnt lgkmcnt(3)
	v_mfma_f32_32x32x16_bf16 v[4:19], v[52:55], v[102:105], v[4:19]
	ds_read2_b64 v[102:105], v85 offset0:80 offset1:82
	s_waitcnt lgkmcnt(3)
	v_mfma_f32_32x32x16_bf16 v[4:19], v[56:59], v[86:89], v[4:19]
	ds_read2_b64 v[86:89], v85 offset0:84 offset1:86
	s_waitcnt lgkmcnt(3)
	v_mfma_f32_32x32x16_bf16 v[4:19], v[64:67], v[94:97], v[4:19]
	ds_read2_b64 v[94:97], v85 offset0:88 offset1:90
	s_waitcnt lgkmcnt(3)
	v_mfma_f32_32x32x16_bf16 v[4:19], v[60:63], v[98:101], v[4:19]
	ds_read2_b64 v[98:101], v85 offset0:92 offset1:94
	s_waitcnt lgkmcnt(3)
	v_mfma_f32_32x32x16_bf16 v[4:19], v[68:71], v[102:105], v[4:19]
	s_waitcnt lgkmcnt(2)
	v_mfma_f32_32x32x16_bf16 v[4:19], v[72:75], v[86:89], v[4:19]
	s_waitcnt lgkmcnt(1)
	v_mfma_f32_32x32x16_bf16 v[4:19], v[76:79], v[94:97], v[4:19]
	s_waitcnt lgkmcnt(0)
	v_mfma_f32_32x32x16_bf16 v[4:19], v[80:83], v[98:101], v[4:19]
	s_nop 11
	v_cvt_pk_bf16_f32 v4, v4, v5
	ds_write_b16 v84, v4 offset:64
	ds_write_b16_d16_hi v84, v4 offset:336
	v_cvt_pk_bf16_f32 v4, v6, v7
	ds_write_b16 v84, v4 offset:608
	ds_write_b16_d16_hi v84, v4 offset:880
	v_cvt_pk_bf16_f32 v4, v8, v9
	ds_write_b16 v84, v4 offset:2240
	ds_write_b16_d16_hi v84, v4 offset:2512
	v_cvt_pk_bf16_f32 v4, v10, v11
	ds_write_b16 v84, v4 offset:2784
	ds_write_b16_d16_hi v84, v4 offset:3056
	v_cvt_pk_bf16_f32 v4, v12, v13
	ds_write_b16 v84, v4 offset:4416
	ds_write_b16_d16_hi v84, v4 offset:4688
	v_cvt_pk_bf16_f32 v4, v14, v15
	ds_write_b16 v84, v4 offset:4960
	ds_write_b16_d16_hi v84, v4 offset:5232
	v_cvt_pk_bf16_f32 v4, v16, v17
	ds_write_b16 v84, v4 offset:6592
	ds_write_b16_d16_hi v84, v4 offset:6864
	v_cvt_pk_bf16_f32 v4, v18, v19
	ds_write_b16 v84, v4 offset:7136
	ds_write_b16_d16_hi v84, v4 offset:7408
	v_mad_u32_u24 v85, v214, s8, v92
	ds_read2_b64 v[4:7], v85 offset1:2
	ds_read2_b64 v[86:89], v85 offset0:4 offset1:6
	ds_read2_b64 v[94:97], v85 offset0:8 offset1:10
	ds_read2_b64 v[98:101], v85 offset0:12 offset1:14
	ds_read2_b64 v[102:105], v85 offset0:16 offset1:18
	s_waitcnt lgkmcnt(4)
	v_mfma_f32_32x32x16_bf16 v[4:19], v[20:23], v[4:7], 0
	s_waitcnt lgkmcnt(3)
	v_mfma_f32_32x32x16_bf16 v[4:19], v[24:27], v[86:89], v[4:19]
	ds_read2_b64 v[86:89], v85 offset0:20 offset1:22
	s_waitcnt lgkmcnt(3)
	v_mfma_f32_32x32x16_bf16 v[4:19], v[32:35], v[94:97], v[4:19]
	ds_read2_b64 v[94:97], v85 offset0:24 offset1:26
	s_waitcnt lgkmcnt(3)
	v_mfma_f32_32x32x16_bf16 v[4:19], v[28:31], v[98:101], v[4:19]
	ds_read2_b64 v[98:101], v85 offset0:28 offset1:30
	s_waitcnt lgkmcnt(3)
	v_mfma_f32_32x32x16_bf16 v[4:19], v[36:39], v[102:105], v[4:19]
	ds_read2_b64 v[102:105], v85 offset0:32 offset1:34
	s_waitcnt lgkmcnt(3)
	v_mfma_f32_32x32x16_bf16 v[4:19], v[40:43], v[86:89], v[4:19]
	ds_read2_b64 v[86:89], v85 offset0:36 offset1:38
	s_waitcnt lgkmcnt(3)
	v_mfma_f32_32x32x16_bf16 v[4:19], v[48:51], v[94:97], v[4:19]
	ds_read2_b64 v[94:97], v85 offset0:40 offset1:42
	s_waitcnt lgkmcnt(3)
	v_mfma_f32_32x32x16_bf16 v[4:19], v[44:47], v[98:101], v[4:19]
	ds_read2_b64 v[98:101], v85 offset0:44 offset1:46
	s_waitcnt lgkmcnt(3)
	v_mfma_f32_32x32x16_bf16 v[4:19], v[52:55], v[102:105], v[4:19]
	ds_read2_b64 v[102:105], v85 offset0:48 offset1:50
	s_waitcnt lgkmcnt(3)
	v_mfma_f32_32x32x16_bf16 v[4:19], v[56:59], v[86:89], v[4:19]
	ds_read2_b64 v[86:89], v85 offset0:52 offset1:54
	s_waitcnt lgkmcnt(3)
	v_mfma_f32_32x32x16_bf16 v[4:19], v[64:67], v[94:97], v[4:19]
	ds_read2_b64 v[94:97], v85 offset0:56 offset1:58
	s_waitcnt lgkmcnt(3)
	v_mfma_f32_32x32x16_bf16 v[4:19], v[60:63], v[98:101], v[4:19]
	ds_read2_b64 v[98:101], v85 offset0:60 offset1:62
	s_waitcnt lgkmcnt(3)
	v_mfma_f32_32x32x16_bf16 v[4:19], v[68:71], v[102:105], v[4:19]
	s_waitcnt lgkmcnt(2)
	v_mfma_f32_32x32x16_bf16 v[4:19], v[72:75], v[86:89], v[4:19]
	s_waitcnt lgkmcnt(1)
	v_mfma_f32_32x32x16_bf16 v[4:19], v[76:79], v[94:97], v[4:19]
	s_waitcnt lgkmcnt(0)
	v_mfma_f32_32x32x16_bf16 v[4:19], v[80:83], v[98:101], v[4:19]
	s_nop 11
	v_cvt_pk_bf16_f32 v4, v4, v5
	ds_write_b16 v84, v4 offset:128
	ds_write_b16_d16_hi v84, v4 offset:400
	v_cvt_pk_bf16_f32 v4, v6, v7
	ds_write_b16 v84, v4 offset:672
	ds_write_b16_d16_hi v84, v4 offset:944
	v_cvt_pk_bf16_f32 v4, v8, v9
	ds_write_b16 v84, v4 offset:2304
	ds_write_b16_d16_hi v84, v4 offset:2576
	v_cvt_pk_bf16_f32 v4, v10, v11
	ds_write_b16 v84, v4 offset:2848
	ds_write_b16_d16_hi v84, v4 offset:3120
	v_cvt_pk_bf16_f32 v4, v12, v13
	ds_write_b16 v84, v4 offset:4480
	ds_write_b16_d16_hi v84, v4 offset:4752
	v_cvt_pk_bf16_f32 v4, v14, v15
	ds_write_b16 v84, v4 offset:5024
	ds_write_b16_d16_hi v84, v4 offset:5296
	v_cvt_pk_bf16_f32 v4, v16, v17
	ds_write_b16 v84, v4 offset:6656
	ds_write_b16_d16_hi v84, v4 offset:6928
	v_cvt_pk_bf16_f32 v4, v18, v19
	ds_write_b16 v84, v4 offset:7200
	ds_write_b16_d16_hi v84, v4 offset:7472
	v_mad_u32_u24 v85, v212, s8, v92
	ds_read2_b64 v[4:7], v85 offset1:2
	ds_read2_b64 v[86:89], v85 offset0:4 offset1:6
	ds_read2_b64 v[94:97], v85 offset0:8 offset1:10
	ds_read2_b64 v[98:101], v85 offset0:12 offset1:14
	ds_read2_b64 v[102:105], v85 offset0:16 offset1:18
	s_waitcnt lgkmcnt(4)
	v_mfma_f32_32x32x16_bf16 v[4:19], v[20:23], v[4:7], 0
	s_waitcnt lgkmcnt(3)
	v_mfma_f32_32x32x16_bf16 v[4:19], v[24:27], v[86:89], v[4:19]
	ds_read2_b64 v[86:89], v85 offset0:20 offset1:22
	s_waitcnt lgkmcnt(3)
	v_mfma_f32_32x32x16_bf16 v[4:19], v[32:35], v[94:97], v[4:19]
	ds_read2_b64 v[94:97], v85 offset0:24 offset1:26
	s_waitcnt lgkmcnt(3)
	v_mfma_f32_32x32x16_bf16 v[4:19], v[28:31], v[98:101], v[4:19]
	ds_read2_b64 v[98:101], v85 offset0:28 offset1:30
	s_waitcnt lgkmcnt(3)
	v_mfma_f32_32x32x16_bf16 v[4:19], v[36:39], v[102:105], v[4:19]
	ds_read2_b64 v[102:105], v85 offset0:32 offset1:34
	s_waitcnt lgkmcnt(3)
	v_mfma_f32_32x32x16_bf16 v[4:19], v[40:43], v[86:89], v[4:19]
	ds_read2_b64 v[86:89], v85 offset0:36 offset1:38
	s_waitcnt lgkmcnt(3)
	v_mfma_f32_32x32x16_bf16 v[4:19], v[48:51], v[94:97], v[4:19]
	ds_read2_b64 v[94:97], v85 offset0:40 offset1:42
	s_waitcnt lgkmcnt(3)
	v_mfma_f32_32x32x16_bf16 v[4:19], v[44:47], v[98:101], v[4:19]
	ds_read2_b64 v[98:101], v85 offset0:44 offset1:46
	s_waitcnt lgkmcnt(3)
	v_mfma_f32_32x32x16_bf16 v[4:19], v[52:55], v[102:105], v[4:19]
	ds_read2_b64 v[102:105], v85 offset0:48 offset1:50
	s_waitcnt lgkmcnt(3)
	v_mfma_f32_32x32x16_bf16 v[4:19], v[56:59], v[86:89], v[4:19]
	ds_read2_b64 v[86:89], v85 offset0:52 offset1:54
	s_waitcnt lgkmcnt(3)
	v_mfma_f32_32x32x16_bf16 v[4:19], v[64:67], v[94:97], v[4:19]
	ds_read2_b64 v[94:97], v85 offset0:56 offset1:58
	s_waitcnt lgkmcnt(3)
	v_mfma_f32_32x32x16_bf16 v[4:19], v[60:63], v[98:101], v[4:19]
	ds_read2_b64 v[98:101], v85 offset0:60 offset1:62
	s_waitcnt lgkmcnt(3)
	v_mfma_f32_32x32x16_bf16 v[4:19], v[68:71], v[102:105], v[4:19]
	s_waitcnt lgkmcnt(2)
	v_mfma_f32_32x32x16_bf16 v[4:19], v[72:75], v[86:89], v[4:19]
	s_waitcnt lgkmcnt(1)
	v_mfma_f32_32x32x16_bf16 v[4:19], v[76:79], v[94:97], v[4:19]
	s_waitcnt lgkmcnt(0)
	v_mfma_f32_32x32x16_bf16 v[4:19], v[80:83], v[98:101], v[4:19]
	s_nop 11
	v_cvt_pk_bf16_f32 v4, v4, v5
	ds_write_b16 v84, v4 offset:192
	ds_write_b16_d16_hi v84, v4 offset:464
	v_cvt_pk_bf16_f32 v4, v6, v7
	ds_write_b16 v84, v4 offset:736
	ds_write_b16_d16_hi v84, v4 offset:1008
	v_cvt_pk_bf16_f32 v4, v8, v9
	ds_write_b16 v84, v4 offset:2368
	ds_write_b16_d16_hi v84, v4 offset:2640
	v_cvt_pk_bf16_f32 v4, v10, v11
	ds_write_b16 v84, v4 offset:2912
	ds_write_b16_d16_hi v84, v4 offset:3184
	v_cvt_pk_bf16_f32 v4, v12, v13
	ds_write_b16 v84, v4 offset:4544
	ds_write_b16_d16_hi v84, v4 offset:4816
	v_cvt_pk_bf16_f32 v4, v14, v15
	ds_write_b16 v84, v4 offset:5088
	ds_write_b16_d16_hi v84, v4 offset:5360
	v_cvt_pk_bf16_f32 v4, v16, v17
	ds_write_b16 v84, v4 offset:6720
	ds_write_b16_d16_hi v84, v4 offset:6992
	v_cvt_pk_bf16_f32 v4, v18, v19
	ds_write_b16 v84, v4 offset:7264
	ds_write_b16_d16_hi v84, v4 offset:7536
	v_mul_u32_u24_e32 v4, 0x110, v210
	v_add3_u32 v6, s61, v4, v2
	ds_read_b128 v[8:11], v6
	s_mulk_i32 s41, 0xc00
	s_mul_hi_u32 s44, s40, 0xc00
	s_waitcnt vmcnt(7)
	v_lshlrev_b32_e32 v14, 16, v160
	v_and_b32_e32 v15, 0xffff0000, v160
	s_waitcnt lgkmcnt(0)
	v_lshlrev_b32_e32 v12, 16, v8
	v_and_b32_e32 v13, 0xffff0000, v8
	s_add_i32 s44, s44, s41
	s_mulk_i32 s40, 0xc00
	v_pk_mul_f32 v[12:13], v[14:15], v[12:13]
	s_add_u32 s40, s36, s40
	v_cvt_pk_bf16_f32 v8, v12, v13
	v_lshlrev_b32_e32 v12, 16, v9
	v_and_b32_e32 v13, 0xffff0000, v9
	v_lshlrev_b32_e32 v14, 16, v161
	v_and_b32_e32 v15, 0xffff0000, v161
	s_addc_u32 s41, s37, s44
	v_pk_mul_f32 v[12:13], v[14:15], v[12:13]
	s_add_u32 s40, s40, s24
	v_mul_u32_u24_e32 v4, 0x600, v210
	v_cvt_pk_bf16_f32 v9, v12, v13
	v_lshlrev_b32_e32 v12, 16, v10
	v_and_b32_e32 v13, 0xffff0000, v10
	v_lshlrev_b32_e32 v14, 16, v162
	v_and_b32_e32 v15, 0xffff0000, v162
	s_addc_u32 s41, s41, 0
	v_lshlrev_b32_e32 v4, 1, v4
	v_mov_b32_e32 v5, v3
	v_pk_mul_f32 v[12:13], v[14:15], v[12:13]
	v_lshl_add_u64 v[4:5], s[40:41], 0, v[4:5]
	v_cvt_pk_bf16_f32 v10, v12, v13
	v_lshlrev_b32_e32 v12, 16, v11
	v_and_b32_e32 v13, 0xffff0000, v11
	v_lshlrev_b32_e32 v14, 16, v163
	v_and_b32_e32 v15, 0xffff0000, v163
	v_lshl_add_u64 v[4:5], v[4:5], 0, v[2:3]
	v_pk_mul_f32 v[12:13], v[14:15], v[12:13]
	s_waitcnt vmcnt(6)
	v_lshlrev_b32_e32 v14, 16, v156
	v_cvt_pk_bf16_f32 v11, v12, v13
	v_add_co_u32_e32 v12, vcc, s21, v4
	v_and_b32_e32 v15, 0xffff0000, v156
	s_nop 0
	v_addc_co_u32_e32 v13, vcc, 0, v5, vcc
	global_store_dwordx4 v[12:13], v[8:11], off offset:2048 sc1
	ds_read_b128 v[8:11], v6 offset:1088
	s_add_i32 s43, s43, s10
	s_add_i32 s42, s42, s93
	s_add_i32 s14, s14, s29
	s_cmpk_lt_i32 s43, 0x100
	s_waitcnt lgkmcnt(0)
	v_lshlrev_b32_e32 v12, 16, v8
	v_and_b32_e32 v13, 0xffff0000, v8
	v_pk_mul_f32 v[12:13], v[14:15], v[12:13]
	v_lshlrev_b32_e32 v14, 16, v157
	v_cvt_pk_bf16_f32 v8, v12, v13
	v_lshlrev_b32_e32 v12, 16, v9
	v_and_b32_e32 v13, 0xffff0000, v9
	v_and_b32_e32 v15, 0xffff0000, v157
	v_pk_mul_f32 v[12:13], v[14:15], v[12:13]
	v_lshlrev_b32_e32 v14, 16, v158
	v_cvt_pk_bf16_f32 v9, v12, v13
	v_lshlrev_b32_e32 v12, 16, v10
	v_and_b32_e32 v13, 0xffff0000, v10
	v_and_b32_e32 v15, 0xffff0000, v158
	v_pk_mul_f32 v[12:13], v[14:15], v[12:13]
	v_lshlrev_b32_e32 v14, 16, v159
	v_cvt_pk_bf16_f32 v10, v12, v13
	v_lshlrev_b32_e32 v12, 16, v11
	v_and_b32_e32 v13, 0xffff0000, v11
	v_and_b32_e32 v15, 0xffff0000, v159
	v_pk_mul_f32 v[12:13], v[14:15], v[12:13]
	s_waitcnt vmcnt(6)
	v_lshlrev_b32_e32 v14, 16, v152
	v_cvt_pk_bf16_f32 v11, v12, v13
	v_add_co_u32_e32 v12, vcc, s2, v4
	v_and_b32_e32 v15, 0xffff0000, v152
	s_nop 0
	v_addc_co_u32_e32 v13, vcc, 0, v5, vcc
	global_store_dwordx4 v[12:13], v[8:11], off offset:2048 sc1
	ds_read_b128 v[8:11], v6 offset:2176
	s_waitcnt lgkmcnt(0)
	v_lshlrev_b32_e32 v12, 16, v8
	v_and_b32_e32 v13, 0xffff0000, v8
	v_pk_mul_f32 v[12:13], v[14:15], v[12:13]
	v_lshlrev_b32_e32 v14, 16, v153
	v_cvt_pk_bf16_f32 v8, v12, v13
	v_lshlrev_b32_e32 v12, 16, v9
	v_and_b32_e32 v13, 0xffff0000, v9
	v_and_b32_e32 v15, 0xffff0000, v153
	v_pk_mul_f32 v[12:13], v[14:15], v[12:13]
	v_lshlrev_b32_e32 v14, 16, v154
	v_cvt_pk_bf16_f32 v9, v12, v13
	v_lshlrev_b32_e32 v12, 16, v10
	v_and_b32_e32 v13, 0xffff0000, v10
	v_and_b32_e32 v15, 0xffff0000, v154
	v_pk_mul_f32 v[12:13], v[14:15], v[12:13]
	v_lshlrev_b32_e32 v14, 16, v155
	v_cvt_pk_bf16_f32 v10, v12, v13
	v_lshlrev_b32_e32 v12, 16, v11
	v_and_b32_e32 v13, 0xffff0000, v11
	v_and_b32_e32 v15, 0xffff0000, v155
	v_pk_mul_f32 v[12:13], v[14:15], v[12:13]
	s_waitcnt vmcnt(6)
	v_lshlrev_b32_e32 v14, 16, v148
	v_cvt_pk_bf16_f32 v11, v12, v13
	v_add_co_u32_e32 v12, vcc, s3, v4
	v_and_b32_e32 v15, 0xffff0000, v148
	s_nop 0
	v_addc_co_u32_e32 v13, vcc, 0, v5, vcc
	global_store_dwordx4 v[12:13], v[8:11], off offset:2048 sc1
	ds_read_b128 v[8:11], v6 offset:3264
	s_waitcnt lgkmcnt(0)
	v_lshlrev_b32_e32 v12, 16, v8
	v_and_b32_e32 v13, 0xffff0000, v8
	v_pk_mul_f32 v[12:13], v[14:15], v[12:13]
	v_lshlrev_b32_e32 v14, 16, v149
	v_cvt_pk_bf16_f32 v8, v12, v13
	v_lshlrev_b32_e32 v12, 16, v9
	v_and_b32_e32 v13, 0xffff0000, v9
	v_and_b32_e32 v15, 0xffff0000, v149
	v_pk_mul_f32 v[12:13], v[14:15], v[12:13]
	v_lshlrev_b32_e32 v14, 16, v150
	v_cvt_pk_bf16_f32 v9, v12, v13
	v_lshlrev_b32_e32 v12, 16, v10
	v_and_b32_e32 v13, 0xffff0000, v10
	v_and_b32_e32 v15, 0xffff0000, v150
	v_pk_mul_f32 v[12:13], v[14:15], v[12:13]
	v_lshlrev_b32_e32 v14, 16, v151
	v_cvt_pk_bf16_f32 v10, v12, v13
	v_lshlrev_b32_e32 v12, 16, v11
	v_and_b32_e32 v13, 0xffff0000, v11
	v_and_b32_e32 v15, 0xffff0000, v151
	v_pk_mul_f32 v[12:13], v[14:15], v[12:13]
	s_waitcnt vmcnt(6)
	v_lshlrev_b32_e32 v14, 16, v144
	v_cvt_pk_bf16_f32 v11, v12, v13
	v_add_co_u32_e32 v12, vcc, s94, v4
	v_and_b32_e32 v15, 0xffff0000, v144
	s_nop 0
	v_addc_co_u32_e32 v13, vcc, 0, v5, vcc
	global_store_dwordx4 v[12:13], v[8:11], off offset:2048 sc1
	ds_read_b128 v[8:11], v6 offset:4352
	s_waitcnt lgkmcnt(0)
	v_lshlrev_b32_e32 v12, 16, v8
	v_and_b32_e32 v13, 0xffff0000, v8
	v_pk_mul_f32 v[12:13], v[14:15], v[12:13]
	v_lshlrev_b32_e32 v14, 16, v145
	v_cvt_pk_bf16_f32 v8, v12, v13
	v_lshlrev_b32_e32 v12, 16, v9
	v_and_b32_e32 v13, 0xffff0000, v9
	v_and_b32_e32 v15, 0xffff0000, v145
	v_pk_mul_f32 v[12:13], v[14:15], v[12:13]
	v_lshlrev_b32_e32 v14, 16, v146
	v_cvt_pk_bf16_f32 v9, v12, v13
	v_lshlrev_b32_e32 v12, 16, v10
	v_and_b32_e32 v13, 0xffff0000, v10
	v_and_b32_e32 v15, 0xffff0000, v146
	v_pk_mul_f32 v[12:13], v[14:15], v[12:13]
	v_lshlrev_b32_e32 v14, 16, v147
	v_cvt_pk_bf16_f32 v10, v12, v13
	v_lshlrev_b32_e32 v12, 16, v11
	v_and_b32_e32 v13, 0xffff0000, v11
	v_and_b32_e32 v15, 0xffff0000, v147
	v_pk_mul_f32 v[12:13], v[14:15], v[12:13]
	s_waitcnt vmcnt(6)
	v_lshlrev_b32_e32 v14, 16, v140
	v_cvt_pk_bf16_f32 v11, v12, v13
	v_add_co_u32_e32 v12, vcc, s97, v4
	v_and_b32_e32 v15, 0xffff0000, v140
	s_nop 0
	v_addc_co_u32_e32 v13, vcc, 0, v5, vcc
	global_store_dwordx4 v[12:13], v[8:11], off offset:2048 sc1
	ds_read_b128 v[8:11], v6 offset:5440
	s_waitcnt lgkmcnt(0)
	v_lshlrev_b32_e32 v12, 16, v8
	v_and_b32_e32 v13, 0xffff0000, v8
	v_pk_mul_f32 v[12:13], v[14:15], v[12:13]
	v_lshlrev_b32_e32 v14, 16, v141
	v_cvt_pk_bf16_f32 v8, v12, v13
	v_lshlrev_b32_e32 v12, 16, v9
	v_and_b32_e32 v13, 0xffff0000, v9
	v_and_b32_e32 v15, 0xffff0000, v141
	v_pk_mul_f32 v[12:13], v[14:15], v[12:13]
	v_lshlrev_b32_e32 v14, 16, v142
	v_cvt_pk_bf16_f32 v9, v12, v13
	v_lshlrev_b32_e32 v12, 16, v10
	v_and_b32_e32 v13, 0xffff0000, v10
	v_and_b32_e32 v15, 0xffff0000, v142
	v_pk_mul_f32 v[12:13], v[14:15], v[12:13]
	v_lshlrev_b32_e32 v14, 16, v143
	v_cvt_pk_bf16_f32 v10, v12, v13
	v_lshlrev_b32_e32 v12, 16, v11
	v_and_b32_e32 v13, 0xffff0000, v11
	v_and_b32_e32 v15, 0xffff0000, v143
	v_pk_mul_f32 v[12:13], v[14:15], v[12:13]
	s_waitcnt vmcnt(6)
	v_lshlrev_b32_e32 v14, 16, v136
	v_cvt_pk_bf16_f32 v11, v12, v13
	v_add_co_u32_e32 v12, vcc, s4, v4
	v_and_b32_e32 v15, 0xffff0000, v136
	s_nop 0
	v_addc_co_u32_e32 v13, vcc, 0, v5, vcc
	global_store_dwordx4 v[12:13], v[8:11], off offset:2048 sc1
	ds_read_b128 v[8:11], v6 offset:6528
	s_waitcnt lgkmcnt(0)
	v_lshlrev_b32_e32 v12, 16, v8
	v_and_b32_e32 v13, 0xffff0000, v8
	v_pk_mul_f32 v[12:13], v[14:15], v[12:13]
	v_lshlrev_b32_e32 v14, 16, v137
	v_cvt_pk_bf16_f32 v8, v12, v13
	v_lshlrev_b32_e32 v12, 16, v9
	v_and_b32_e32 v13, 0xffff0000, v9
	v_and_b32_e32 v15, 0xffff0000, v137
	v_pk_mul_f32 v[12:13], v[14:15], v[12:13]
	v_lshlrev_b32_e32 v14, 16, v138
	v_cvt_pk_bf16_f32 v9, v12, v13
	v_lshlrev_b32_e32 v12, 16, v10
	v_and_b32_e32 v13, 0xffff0000, v10
	v_and_b32_e32 v15, 0xffff0000, v138
	v_pk_mul_f32 v[12:13], v[14:15], v[12:13]
	v_lshlrev_b32_e32 v14, 16, v139
	v_cvt_pk_bf16_f32 v10, v12, v13
	v_lshlrev_b32_e32 v12, 16, v11
	v_and_b32_e32 v13, 0xffff0000, v11
	v_and_b32_e32 v15, 0xffff0000, v139
	v_pk_mul_f32 v[12:13], v[14:15], v[12:13]
	s_nop 0
	v_cvt_pk_bf16_f32 v11, v12, v13
	v_add_co_u32_e32 v12, vcc, s22, v4
	s_nop 1
	v_addc_co_u32_e32 v13, vcc, 0, v5, vcc
	global_store_dwordx4 v[12:13], v[8:11], off offset:2048 sc1
	ds_read_b128 v[6:9], v6 offset:7616
	s_waitcnt vmcnt(7)
	v_lshlrev_b32_e32 v12, 16, v132
	v_and_b32_e32 v13, 0xffff0000, v132
	v_add_co_u32_e32 v4, vcc, 0xc615000, v4
	s_waitcnt lgkmcnt(0)
	v_lshlrev_b32_e32 v10, 16, v6
	v_and_b32_e32 v11, 0xffff0000, v6
	v_pk_mul_f32 v[10:11], v[12:13], v[10:11]
	v_lshlrev_b32_e32 v12, 16, v133
	v_cvt_pk_bf16_f32 v6, v10, v11
	v_lshlrev_b32_e32 v10, 16, v7
	v_and_b32_e32 v11, 0xffff0000, v7
	v_and_b32_e32 v13, 0xffff0000, v133
	v_pk_mul_f32 v[10:11], v[12:13], v[10:11]
	v_lshlrev_b32_e32 v12, 16, v134
	v_cvt_pk_bf16_f32 v7, v10, v11
	v_lshlrev_b32_e32 v10, 16, v8
	v_and_b32_e32 v11, 0xffff0000, v8
	v_and_b32_e32 v13, 0xffff0000, v134
	v_pk_mul_f32 v[10:11], v[12:13], v[10:11]
	v_lshlrev_b32_e32 v12, 16, v135
	v_cvt_pk_bf16_f32 v8, v10, v11
	v_lshlrev_b32_e32 v10, 16, v9
	v_and_b32_e32 v11, 0xffff0000, v9
	v_and_b32_e32 v13, 0xffff0000, v135
	v_pk_mul_f32 v[10:11], v[12:13], v[10:11]
	v_addc_co_u32_e32 v5, vcc, 0, v5, vcc
	v_cvt_pk_bf16_f32 v9, v10, v11
	global_store_dwordx4 v[4:5], v[6:9], off offset:2048 sc1
	s_barrier
	s_cbranch_scc1 .LBB0_758
	s_branch .LBB0_681
